# 12c: per-token sum-of-squares wave reduction on DPP (6 ds_bpermute round trips removed), total taken from lane 63
# speedup vs baseline: 1.0214x; 1.0067x over previous
; DI int otid() { int t = threadIdx.x; asm volatile("" : "+v"(t)); return t; }
; DI void peer_v_phase(const Params& p) {
;   const int tid_ = otid();
;   const int lane = tid_ & 63, wave = tid_ >> 6;
;   const int g = blockIdx.x & 7, rank = blockIdx.x >> 3, nrank = gridDim.x >> 3;
;   if (rank >= nrank) return;
;   const int q = lane >> 3, s = lane & 7;
;   const unsigned char* Vb = (const unsigned char*)(p.ws + OFF_VB) + (size_t)g * (16384 * 128) + 16 * s;
;   const int* EID = (const int*)(p.ws + OFF_EID);
;   const float* W = (const float*)(p.ws + OFF_W);
;   float* SSP = (float*)(p.ws + OFF_SSP) + (size_t)g * T_TOK;
;   const int first = rank * 4 + wave, stride = nrank * 4;
;   const int n = (T_TOK - first + stride - 1) / stride;
;   auto tokof = [&](int k) { return first + (k < n ? k : n - 1) * stride; };
.LBB0_1473:
	s_or_b64 exec, exec, s[4:5]
	v_mov_b32_e32 v62, v192
	s_andn2_b64 vcc, exec, s[10:11]
	s_waitcnt lgkmcnt(0)
	s_barrier
	s_cbranch_vccnz .LBB0_1483
	s_lshl_b32 s18, s0, 2
	v_cvt_f32_u32_e32 v0, s18
	v_ashrrev_i32_e32 v1, 6, v62
	v_lshl_add_u32 v194, s1, 2, v1
	v_sub_u32_e32 v1, s18, v194
	v_rcp_iflag_f32_e32 v0, v0
	v_add_u32_e32 v1, 0x3fff, v1
	s_sub_i32 s1, 0, s18
	v_sub_u32_e32 v3, 0, v1
	v_mul_f32_e32 v0, 0x4f7ffffe, v0
	v_cvt_u32_f32_e32 v0, v0
	v_ashrrev_i32_e32 v2, 31, v1
	v_max_i32_e32 v1, v1, v3
	v_mul_lo_u32 v3, s1, v0
	v_mul_hi_u32 v3, v0, v3
	v_add_u32_e32 v0, v0, v3
	v_mul_hi_u32 v0, v1, v0
	v_mul_lo_u32 v3, v0, s18
	v_sub_u32_e32 v1, v1, v3
	v_add_u32_e32 v4, 1, v0
	v_cmp_le_u32_e32 vcc, s18, v1
	v_subrev_u32_e32 v3, s18, v1
	s_nop 0
	v_cndmask_b32_e32 v0, v0, v4, vcc
	v_cndmask_b32_e32 v1, v1, v3, vcc
	v_add_u32_e32 v3, 1, v0
	v_cmp_le_u32_e32 vcc, s18, v1
	s_nop 1
	v_cndmask_b32_e32 v0, v0, v3, vcc
	v_xor_b32_e32 v0, v0, v2
	v_sub_u32_e32 v193, v0, v2
	v_cmp_lt_i32_e32 vcc, 0, v193
	s_and_saveexec_b64 s[10:11], vcc
	s_cbranch_execz .LBB0_1482
; DI void peer_v_phase(const Params& p) {
;     ...
;   const int first = rank * 4 + wave, stride = nrank * 4;
;   const int n = (T_TOK - first + stride - 1) / stride;
;   auto tokof = [&](int k) { return first + (k < n ? k : n - 1) * stride; };
;   auto gather = [&](PeerVRows& r, const int* e, int tok) {
; #pragma unroll
;     for (int i = 0; i < 16; ++i) r.v[i] = *(const u32x4*)(Vb + (size_t)e[i] * 128);
;     const float4* wp = (const float4*)(W + (size_t)tok * 128 + 16 * q);
; #pragma unroll
;     for (int j = 0; j < 4; ++j) r.w[j] = wp[j];
;   };
;   auto compute = [&](const PeerVRows& r, int tok) {
;     f32x2 o2[8];
; #pragma unroll
;     for (int k = 0; k < 8; ++k) { o2[k][0] = 0.f; o2[k][1] = 0.f; }
; #pragma unroll
;     for (int i = 0; i < 16; ++i) {
;       const float wi = (i & 3) == 0 ? r.w[i >> 2].x : (i & 3) == 1 ? r.w[i >> 2].y : (i & 3) == 2 ? r.w[i >> 2].z : r.w[i >> 2].w;
;       const f32x2 w2 = {wi, wi};
; #pragma unroll
;       for (int j = 0; j < 4; ++j) {
;         const f32x2 lo = __builtin_amdgcn_cvt_pk_f32_fp8((int)r.v[i][j], false);
;         const f32x2 hi = __builtin_amdgcn_cvt_pk_f32_fp8((int)r.v[i][j], true);
;         o2[2 * j] = __builtin_elementwise_fma(lo, w2, o2[2 * j]);
;         o2[2 * j + 1] = __builtin_elementwise_fma(hi, w2, o2[2 * j + 1]);
;       }
;     }
;     float o[16];
; #pragma unroll
;     for (int k = 0; k < 8; ++k) { o[2 * k] = o2[k][0]; o[2 * k + 1] = o2[k][1]; }
;     float r8[8], r4[4], r2[2];
; #pragma unroll
;     for (int k = 0; k < 8; ++k) {
;       const float keep = (lane & 32) ? o[k + 8] : o[k], send = (lane & 32) ? o[k] : o[k + 8];
;       r8[k] = keep + __shfl_xor(send, 32);
;     }
; #pragma unroll
;     for (int k = 0; k < 4; ++k) {
;       const float keep = (lane & 16) ? r8[k + 4] : r8[k], send = (lane & 16) ? r8[k] : r8[k + 4];
;       r4[k] = keep + __shfl_xor(send, 16);
;     }
; #pragma unroll
;     for (int k = 0; k < 2; ++k) {
;       const float keep = (lane & 8) ? r4[k + 2] : r4[k], send = (lane & 8) ? r4[k] : r4[k + 2];
;       r2[k] = keep + __shfl_xor(send, 8);
;     }
;     float* xr = p.out + (size_t)tok * 1024 + 128 * g + 16 * s + 2 * q;
;     float2 y = *(const float2*)xr;
;     y.x += r2[0]; y.y += r2[1];
;     *(float2*)xr = y;
;     const float ss = wave_sum(y.x * y.x + y.y * y.y);
;     if (lane == 0) SSP[tok] = ss;
;   };
;   int ea[16], eb[16];
;   PeerVRows ga, gb;
	v_lshlrev_b32_e32 v0, 3, v62
	v_ashrrev_i32_e32 v195, 31, v194
	v_mov_b32_e32 v61, 0
	v_and_b32_e32 v72, 0x1c0, v0
	v_lshlrev_b64 v[0:1], 9, v[194:195]
	v_mov_b32_e32 v73, v61
	v_lshl_add_u64 v[2:3], s[86:87], 0, v[0:1]
	v_lshl_add_u64 v[2:3], v[2:3], 0, v[72:73]
	global_load_dwordx4 v[4:7], v[2:3], off offset:48
	global_load_dwordx4 v[8:11], v[2:3], off offset:32
	global_load_dwordx4 v[16:19], v[2:3], off offset:16
	global_load_dwordx4 v[68:71], v[2:3], off
	s_and_b32 s8, s80, 7
	s_lshl_b32 s1, s8, 21
	v_lshlrev_b32_e32 v2, 4, v62
	s_add_u32 s2, s86, s1
	v_and_b32_e32 v60, 0x70, v2
	s_addc_u32 s3, s87, 0
	v_lshl_add_u64 v[2:3], s[2:3], 0, v[60:61]
	s_add_u32 s2, s86, 0x5000000
	s_addc_u32 s3, s87, 0
	v_lshl_add_u64 v[0:1], s[2:3], 0, v[0:1]
	s_mov_b64 s[4:5], 0x9000000
	v_lshl_add_u64 v[20:21], v[0:1], 0, v[72:73]
	v_lshl_add_u64 v[196:197], v[2:3], 0, s[4:5]
	global_load_dwordx4 v[0:3], v[20:21], off offset:48
	global_load_dwordx4 v[12:15], v[20:21], off offset:32
	global_load_dwordx4 v[28:31], v[20:21], off offset:16
	global_load_dwordx4 v[52:55], v[20:21], off
	v_add_u32_e32 v195, -1, v193
	v_mov_b32_e32 v63, s18
	v_cmp_ne_u32_e32 vcc, 0, v195
	s_lshl_b32 s1, s8, 16
	v_lshl_add_u64 v[200:201], s[2:3], 0, v[72:73]
	v_cndmask_b32_e32 v63, 0, v63, vcc
	s_add_u32 s1, s86, s1
	s_addc_u32 s4, s87, 0
	s_add_u32 s12, s1, 0x5800000
	s_addc_u32 s13, s4, 0
	s_lshl_b32 s8, s8, 9
	s_add_u32 s8, s84, s8
	s_addc_u32 s9, s85, 0
	v_lshlrev_b32_e32 v60, 2, v60
	s_mov_b32 s1, 3
	v_lshl_add_u64 v[198:199], s[86:87], 0, v[72:73]
	s_lshl_b32 s0, s0, 3
	s_mov_b64 s[14:15], 0
	v_mov_b32_e32 v204, v194
	s_waitcnt vmcnt(7)
	v_ashrrev_i32_e32 v21, 31, v7
	v_mov_b32_e32 v20, v7
	v_ashrrev_i32_e32 v7, 31, v6
	v_ashrrev_i32_e32 v23, 31, v5
	v_mov_b32_e32 v22, v5
	v_ashrrev_i32_e32 v5, 31, v4
	s_waitcnt vmcnt(4)
	v_ashrrev_i32_e32 v75, 31, v71
	v_mov_b32_e32 v74, v71
	v_ashrrev_i32_e32 v71, 31, v70
	v_ashrrev_i32_e32 v25, 31, v11
	v_mov_b32_e32 v24, v11
	v_ashrrev_i32_e32 v11, 31, v10
	v_ashrrev_i32_e32 v27, 31, v9
	v_mov_b32_e32 v26, v9
	v_ashrrev_i32_e32 v9, 31, v8
	v_ashrrev_i32_e32 v33, 31, v19
	v_mov_b32_e32 v32, v19
	v_ashrrev_i32_e32 v19, 31, v18
	v_ashrrev_i32_e32 v35, 31, v17
	v_mov_b32_e32 v34, v17
	v_ashrrev_i32_e32 v17, 31, v16
	v_lshlrev_b64 v[6:7], 7, v[6:7]
	v_lshlrev_b64 v[20:21], 7, v[20:21]
	v_lshlrev_b64 v[4:5], 7, v[4:5]
	v_lshlrev_b64 v[22:23], 7, v[22:23]
	v_lshlrev_b64 v[70:71], 7, v[70:71]
	v_lshlrev_b64 v[74:75], 7, v[74:75]
	v_lshlrev_b64 v[10:11], 7, v[10:11]
	v_lshlrev_b64 v[24:25], 7, v[24:25]
	v_lshlrev_b64 v[8:9], 7, v[8:9]
	v_lshlrev_b64 v[26:27], 7, v[26:27]
	v_lshlrev_b64 v[18:19], 7, v[18:19]
	v_lshlrev_b64 v[32:33], 7, v[32:33]
	v_lshlrev_b64 v[16:17], 7, v[16:17]
	v_lshlrev_b64 v[34:35], 7, v[34:35]
	v_lshl_add_u64 v[76:77], v[196:197], 0, v[20:21]
	v_lshl_add_u64 v[78:79], v[196:197], 0, v[6:7]
	v_lshl_add_u64 v[80:81], v[196:197], 0, v[22:23]
	v_lshl_add_u64 v[82:83], v[196:197], 0, v[4:5]
	v_lshl_add_u64 v[74:75], v[196:197], 0, v[74:75]
	v_lshl_add_u64 v[70:71], v[196:197], 0, v[70:71]
	v_lshl_add_u64 v[84:85], v[196:197], 0, v[24:25]
	v_lshl_add_u64 v[86:87], v[196:197], 0, v[10:11]
	v_lshl_add_u64 v[88:89], v[196:197], 0, v[26:27]
	v_lshl_add_u64 v[90:91], v[196:197], 0, v[8:9]
	v_lshl_add_u64 v[92:93], v[196:197], 0, v[32:33]
	v_lshl_add_u64 v[94:95], v[196:197], 0, v[18:19]
	v_lshl_add_u64 v[96:97], v[196:197], 0, v[34:35]
	v_lshl_add_u64 v[98:99], v[196:197], 0, v[16:17]
	global_load_dwordx4 v[4:7], v[76:77], off
	global_load_dwordx4 v[8:11], v[78:79], off
	global_load_dwordx4 v[16:19], v[80:81], off
	global_load_dwordx4 v[20:23], v[82:83], off
	global_load_dwordx4 v[24:27], v[84:85], off
	global_load_dwordx4 v[32:35], v[86:87], off
	global_load_dwordx4 v[36:39], v[88:89], off
	global_load_dwordx4 v[40:43], v[90:91], off
	global_load_dwordx4 v[44:47], v[92:93], off
	global_load_dwordx4 v[48:51], v[94:95], off
	global_load_dwordx4 v[56:59], v[96:97], off
	global_load_dwordx4 v[64:67], v[98:99], off
	global_load_dwordx4 v[76:79], v[74:75], off
	global_load_dwordx4 v[80:83], v[70:71], off
	v_ashrrev_i32_e32 v71, 31, v69
	v_mov_b32_e32 v70, v69
	v_ashrrev_i32_e32 v69, 31, v68
	v_lshlrev_b64 v[68:69], 7, v[68:69]
	v_lshlrev_b64 v[70:71], 7, v[70:71]
	v_lshl_add_u64 v[70:71], v[196:197], 0, v[70:71]
	v_lshl_add_u64 v[68:69], v[196:197], 0, v[68:69]
	global_load_dwordx4 v[84:87], v[70:71], off
	global_load_dwordx4 v[88:91], v[68:69], off
	v_add_u32_e32 v68, v63, v194
	v_ashrrev_i32_e32 v69, 31, v68
	v_lshlrev_b64 v[68:69], 9, v[68:69]
	v_lshl_add_u64 v[68:69], s[86:87], 0, v[68:69]
	v_lshl_add_u64 v[68:69], v[68:69], 0, v[72:73]
	global_load_dwordx4 v[96:99], v[68:69], off offset:48
	global_load_dwordx4 v[108:111], v[68:69], off offset:32
	global_load_dwordx4 v[116:119], v[68:69], off offset:16
	global_load_dwordx4 v[132:135], v[68:69], off
	v_and_b32_e32 v68, 32, v62
	v_cmp_eq_u32_e32 vcc, 0, v68
	v_mbcnt_lo_u32_b32 v68, -1, 0
	v_mbcnt_hi_u32_b32 v68, -1, v68
	v_and_b32_e32 v70, 64, v68
	v_xor_b32_e32 v69, 32, v68
	v_add_u32_e32 v70, 64, v70
	v_cmp_lt_i32_e64 s[2:3], v69, v70
	v_and_b32_e32 v63, 63, v62
	s_nop 0
	v_cndmask_b32_e64 v69, v68, v69, s[2:3]
	v_lshlrev_b32_e32 v210, 2, v69
	v_and_b32_e32 v69, 16, v62
	v_cmp_eq_u32_e64 s[2:3], 0, v69
	v_xor_b32_e32 v69, 16, v68
	v_cmp_lt_i32_e64 s[4:5], v69, v70
	s_nop 1
	v_cndmask_b32_e64 v69, v68, v69, s[4:5]
	v_lshlrev_b32_e32 v211, 2, v69
	v_and_b32_e32 v69, 8, v62
	v_cmp_eq_u32_e64 s[4:5], 0, v69
	v_xor_b32_e32 v69, 8, v68
	v_cmp_lt_i32_e64 s[6:7], v69, v70
	s_nop 1
	v_cndmask_b32_e64 v69, v68, v69, s[6:7]
	v_lshlrev_b32_e32 v212, 2, v69
	v_xor_b32_e32 v69, 4, v68
	v_cmp_lt_i32_e64 s[6:7], v69, v70
	s_nop 1
	v_cndmask_b32_e64 v69, v68, v69, s[6:7]
	v_lshlrev_b32_e32 v213, 2, v69
	v_xor_b32_e32 v69, 2, v68
	v_cmp_lt_i32_e64 s[6:7], v69, v70
	s_nop 1
	v_cndmask_b32_e64 v69, v68, v69, s[6:7]
	v_lshlrev_b32_e32 v214, 2, v69
	v_xor_b32_e32 v69, 1, v68
	v_cmp_lt_i32_e64 s[6:7], v69, v70
	s_nop 1
	v_cndmask_b32_e64 v68, v68, v69, s[6:7]
	v_lshlrev_b32_e32 v215, 2, v68
	v_lshl_add_u64 v[68:69], s[8:9], 0, v[60:61]
	v_and_b32_e32 v60, 56, v62
	v_cmp_eq_u32_e64 s[6:7], 63, v63
	v_lshl_add_u64 v[202:203], v[68:69], 0, v[60:61]
	s_branch .LBB0_1477

; DI void peer_v_phase(const Params& p) {
;     ...
;   auto gather = [&](PeerVRows& r, const int* e, int tok) {
; #pragma unroll
;     for (int i = 0; i < 16; ++i) r.v[i] = *(const u32x4*)(Vb + (size_t)e[i] * 128);
;     const float4* wp = (const float4*)(W + (size_t)tok * 128 + 16 * q);
; #pragma unroll
;     for (int j = 0; j < 4; ++j) r.w[j] = wp[j];
;   };
;   auto compute = [&](const PeerVRows& r, int tok) {
;     f32x2 o2[8];
; #pragma unroll
;     for (int k = 0; k < 8; ++k) { o2[k][0] = 0.f; o2[k][1] = 0.f; }
; #pragma unroll
;     for (int i = 0; i < 16; ++i) {
;       const float wi = (i & 3) == 0 ? r.w[i >> 2].x : (i & 3) == 1 ? r.w[i >> 2].y : (i & 3) == 2 ? r.w[i >> 2].z : r.w[i >> 2].w;
;       const f32x2 w2 = {wi, wi};
; #pragma unroll
;       for (int j = 0; j < 4; ++j) {
;         const f32x2 lo = __builtin_amdgcn_cvt_pk_f32_fp8((int)r.v[i][j], false);
;         const f32x2 hi = __builtin_amdgcn_cvt_pk_f32_fp8((int)r.v[i][j], true);
;         o2[2 * j] = __builtin_elementwise_fma(lo, w2, o2[2 * j]);
;         o2[2 * j + 1] = __builtin_elementwise_fma(hi, w2, o2[2 * j + 1]);
;       }
;     }
;     ...
;   for (int k = 0; k < n; k += 2) {
;     peer_load_e(ea, EID, tokof(k + 2), q);
;     gather(gb, eb, tokof(k + 1));
;     __builtin_amdgcn_sched_barrier(0);
;     compute(ga, tokof(k));
.LBB0_1477:
	s_add_i32 s19, s1, -1
	v_min_i32_e32 v60, s19, v195
	s_waitcnt lgkmcnt(0)
	v_mad_u64_u32 v[60:61], s[8:9], v60, s18, v[194:195]
	v_ashrrev_i32_e32 v61, 31, v60
	v_lshlrev_b64 v[208:209], 9, v[60:61]
	v_lshl_add_u64 v[60:61], v[198:199], 0, v[208:209]
	s_add_i32 s16, s1, -2
	global_load_dwordx4 v[172:175], v[60:61], off offset:48
	global_load_dwordx4 v[176:179], v[60:61], off offset:32
	global_load_dwordx4 v[184:187], v[60:61], off offset:16
	global_load_dwordx4 v[188:191], v[60:61], off
	v_min_i32_e32 v60, s16, v195
	v_mad_u64_u32 v[206:207], s[8:9], v60, s18, v[194:195]
	s_waitcnt vmcnt(4)
	v_ashrrev_i32_e32 v61, 31, v132
	v_mov_b32_e32 v60, v132
	v_ashrrev_i32_e32 v63, 31, v133
	v_mov_b32_e32 v62, v133
	v_lshlrev_b64 v[60:61], 7, v[60:61]
	v_lshlrev_b64 v[62:63], 7, v[62:63]
	v_lshl_add_u64 v[60:61], v[196:197], 0, v[60:61]
	v_lshl_add_u64 v[62:63], v[196:197], 0, v[62:63]
	global_load_dwordx4 v[168:171], v[60:61], off
	global_load_dwordx4 v[164:167], v[62:63], off
	v_ashrrev_i32_e32 v61, 31, v134
	v_mov_b32_e32 v60, v134
	v_ashrrev_i32_e32 v63, 31, v135
	v_mov_b32_e32 v62, v135
	v_lshlrev_b64 v[60:61], 7, v[60:61]
	v_lshlrev_b64 v[62:63], 7, v[62:63]
	v_lshl_add_u64 v[60:61], v[196:197], 0, v[60:61]
	v_lshl_add_u64 v[62:63], v[196:197], 0, v[62:63]
	global_load_dwordx4 v[160:163], v[60:61], off
	global_load_dwordx4 v[152:155], v[62:63], off
	v_ashrrev_i32_e32 v61, 31, v116
	v_mov_b32_e32 v60, v116
	v_ashrrev_i32_e32 v63, 31, v117
	v_mov_b32_e32 v62, v117
	v_lshlrev_b64 v[60:61], 7, v[60:61]
	v_lshlrev_b64 v[62:63], 7, v[62:63]
	v_lshl_add_u64 v[60:61], v[196:197], 0, v[60:61]
	v_lshl_add_u64 v[62:63], v[196:197], 0, v[62:63]
	global_load_dwordx4 v[148:151], v[60:61], off
	global_load_dwordx4 v[144:147], v[62:63], off
	v_ashrrev_i32_e32 v61, 31, v118
	v_mov_b32_e32 v60, v118
	v_ashrrev_i32_e32 v63, 31, v119
	v_mov_b32_e32 v62, v119
	v_lshlrev_b64 v[60:61], 7, v[60:61]
	v_lshlrev_b64 v[62:63], 7, v[62:63]
	v_lshl_add_u64 v[60:61], v[196:197], 0, v[60:61]
	v_lshl_add_u64 v[62:63], v[196:197], 0, v[62:63]
	global_load_dwordx4 v[140:143], v[60:61], off
	global_load_dwordx4 v[136:139], v[62:63], off
	v_ashrrev_i32_e32 v61, 31, v108
	v_mov_b32_e32 v60, v108
	v_ashrrev_i32_e32 v63, 31, v109
	v_mov_b32_e32 v62, v109
	v_lshlrev_b64 v[60:61], 7, v[60:61]
	v_lshlrev_b64 v[62:63], 7, v[62:63]
	v_lshl_add_u64 v[60:61], v[196:197], 0, v[60:61]
	v_lshl_add_u64 v[62:63], v[196:197], 0, v[62:63]
	global_load_dwordx4 v[128:131], v[60:61], off
	global_load_dwordx4 v[120:123], v[62:63], off
	v_ashrrev_i32_e32 v61, 31, v110
	v_mov_b32_e32 v60, v110
	v_ashrrev_i32_e32 v63, 31, v111
	v_mov_b32_e32 v62, v111
	v_lshlrev_b64 v[60:61], 7, v[60:61]
	v_lshlrev_b64 v[62:63], 7, v[62:63]
	v_lshl_add_u64 v[60:61], v[196:197], 0, v[60:61]
	v_lshl_add_u64 v[62:63], v[196:197], 0, v[62:63]
	global_load_dwordx4 v[112:115], v[60:61], off
	global_load_dwordx4 v[104:107], v[62:63], off
	v_ashrrev_i32_e32 v61, 31, v96
	v_mov_b32_e32 v60, v96
	v_ashrrev_i32_e32 v63, 31, v97
	v_mov_b32_e32 v62, v97
	v_lshlrev_b64 v[60:61], 7, v[60:61]
	v_lshlrev_b64 v[62:63], 7, v[62:63]
	v_lshl_add_u64 v[60:61], v[196:197], 0, v[60:61]
	v_lshl_add_u64 v[62:63], v[196:197], 0, v[62:63]
	global_load_dwordx4 v[100:103], v[60:61], off
	global_load_dwordx4 v[92:95], v[62:63], off
	v_ashrrev_i32_e32 v61, 31, v98
	v_mov_b32_e32 v60, v98
	v_ashrrev_i32_e32 v63, 31, v99
	v_mov_b32_e32 v62, v99
	v_ashrrev_i32_e32 v207, 31, v206
	v_lshlrev_b64 v[60:61], 7, v[60:61]
	v_lshlrev_b64 v[62:63], 7, v[62:63]
	v_lshlrev_b64 v[72:73], 9, v[206:207]
	v_lshl_add_u64 v[60:61], v[196:197], 0, v[60:61]
	v_lshl_add_u64 v[62:63], v[196:197], 0, v[62:63]
	v_lshl_add_u64 v[96:97], v[200:201], 0, v[72:73]
	global_load_dwordx4 v[68:71], v[60:61], off
	s_nop 0
	global_load_dwordx4 v[60:63], v[62:63], off
	s_nop 0
	global_load_dwordx4 v[72:75], v[96:97], off offset:48
	global_load_dwordx4 v[124:127], v[96:97], off offset:32
	global_load_dwordx4 v[156:159], v[96:97], off offset:16
	global_load_dwordx4 v[180:183], v[96:97], off
	v_cvt_pk_f32_fp8_e32 v[96:97], v88
	v_cvt_pk_f32_fp8_sdwa v[98:99], v88 src0_sel:WORD_1
	v_cvt_pk_f32_fp8_e32 v[108:109], v89
	v_cvt_pk_f32_fp8_sdwa v[88:89], v89 src0_sel:WORD_1
	v_cvt_pk_f32_fp8_e32 v[132:133], v84
	v_cvt_pk_f32_fp8_sdwa v[134:135], v84 src0_sel:WORD_1
	v_cvt_pk_f32_fp8_e32 v[216:217], v85
	v_cvt_pk_f32_fp8_sdwa v[84:85], v85 src0_sel:WORD_1
	v_pk_fma_f32 v[96:97], v[96:97], v[52:53], 0 op_sel_hi:[1,0,0]
	v_pk_fma_f32 v[98:99], v[98:99], v[52:53], 0 op_sel_hi:[1,0,0]
	v_pk_fma_f32 v[88:89], v[88:89], v[52:53], 0 op_sel_hi:[1,0,0]
	v_cvt_pk_f32_fp8_e32 v[110:111], v90
	v_cvt_pk_f32_fp8_sdwa v[116:117], v90 src0_sel:WORD_1
	v_cvt_pk_f32_fp8_e32 v[118:119], v91
	v_cvt_pk_f32_fp8_sdwa v[90:91], v91 src0_sel:WORD_1
	v_pk_fma_f32 v[96:97], v[132:133], v[52:53], v[96:97] op_sel:[0,1,0]
	v_pk_fma_f32 v[98:99], v[134:135], v[52:53], v[98:99] op_sel:[0,1,0]
	v_pk_fma_f32 v[84:85], v[84:85], v[52:53], v[88:89] op_sel:[0,1,0]
	v_cvt_pk_f32_fp8_e32 v[88:89], v86
	v_cvt_pk_f32_fp8_sdwa v[132:133], v86 src0_sel:WORD_1
	v_cvt_pk_f32_fp8_e32 v[134:135], v87
	v_cvt_pk_f32_fp8_sdwa v[86:87], v87 src0_sel:WORD_1
	v_pk_fma_f32 v[108:109], v[108:109], v[52:53], 0 op_sel_hi:[1,0,0]
	v_pk_fma_f32 v[110:111], v[110:111], v[52:53], 0 op_sel_hi:[1,0,0]
	v_pk_fma_f32 v[116:117], v[116:117], v[52:53], 0 op_sel_hi:[1,0,0]
	v_pk_fma_f32 v[118:119], v[118:119], v[52:53], 0 op_sel_hi:[1,0,0]
	v_pk_fma_f32 v[90:91], v[90:91], v[52:53], 0 op_sel_hi:[1,0,0]
	v_pk_fma_f32 v[108:109], v[216:217], v[52:53], v[108:109] op_sel:[0,1,0]
	v_pk_fma_f32 v[88:89], v[88:89], v[52:53], v[110:111] op_sel:[0,1,0]
; DI void peer_v_phase(const Params& p) {
;     ...
; #pragma unroll
;     for (int i = 0; i < 16; ++i) {
;       const float wi = (i & 3) == 0 ? r.w[i >> 2].x : (i & 3) == 1 ? r.w[i >> 2].y : (i & 3) == 2 ? r.w[i >> 2].z : r.w[i >> 2].w;
;       const f32x2 w2 = {wi, wi};
; #pragma unroll
;       for (int j = 0; j < 4; ++j) {
;         const f32x2 lo = __builtin_amdgcn_cvt_pk_f32_fp8((int)r.v[i][j], false);
;         const f32x2 hi = __builtin_amdgcn_cvt_pk_f32_fp8((int)r.v[i][j], true);
;         o2[2 * j] = __builtin_elementwise_fma(lo, w2, o2[2 * j]);
;         o2[2 * j + 1] = __builtin_elementwise_fma(hi, w2, o2[2 * j + 1]);
;       }
;     }
	v_pk_fma_f32 v[110:111], v[132:133], v[52:53], v[116:117] op_sel:[0,1,0]
	v_pk_fma_f32 v[116:117], v[134:135], v[52:53], v[118:119] op_sel:[0,1,0]
	v_pk_fma_f32 v[52:53], v[86:87], v[52:53], v[90:91] op_sel:[0,1,0]
	v_cvt_pk_f32_fp8_e32 v[86:87], v80
	v_cvt_pk_f32_fp8_sdwa v[90:91], v80 src0_sel:WORD_1
	v_cvt_pk_f32_fp8_e32 v[118:119], v81
	v_cvt_pk_f32_fp8_sdwa v[80:81], v81 src0_sel:WORD_1
	v_pk_fma_f32 v[86:87], v[86:87], v[54:55], v[96:97] op_sel_hi:[1,0,1]
	v_pk_fma_f32 v[90:91], v[90:91], v[54:55], v[98:99] op_sel_hi:[1,0,1]
	v_pk_fma_f32 v[96:97], v[118:119], v[54:55], v[108:109] op_sel_hi:[1,0,1]
	v_pk_fma_f32 v[80:81], v[80:81], v[54:55], v[84:85] op_sel_hi:[1,0,1]
	v_cvt_pk_f32_fp8_e32 v[84:85], v82
	v_cvt_pk_f32_fp8_sdwa v[98:99], v82 src0_sel:WORD_1
	v_cvt_pk_f32_fp8_e32 v[108:109], v83
	v_cvt_pk_f32_fp8_sdwa v[82:83], v83 src0_sel:WORD_1
	v_pk_fma_f32 v[84:85], v[84:85], v[54:55], v[88:89] op_sel_hi:[1,0,1]
	v_pk_fma_f32 v[88:89], v[98:99], v[54:55], v[110:111] op_sel_hi:[1,0,1]
	v_pk_fma_f32 v[98:99], v[108:109], v[54:55], v[116:117] op_sel_hi:[1,0,1]
	v_pk_fma_f32 v[52:53], v[82:83], v[54:55], v[52:53] op_sel_hi:[1,0,1]
	v_cvt_pk_f32_fp8_e32 v[82:83], v76
	v_cvt_pk_f32_fp8_sdwa v[108:109], v76 src0_sel:WORD_1
	v_cvt_pk_f32_fp8_e32 v[110:111], v77
	v_cvt_pk_f32_fp8_sdwa v[76:77], v77 src0_sel:WORD_1
	v_pk_fma_f32 v[82:83], v[82:83], v[54:55], v[86:87] op_sel:[0,1,0]
	v_pk_fma_f32 v[86:87], v[108:109], v[54:55], v[90:91] op_sel:[0,1,0]
	v_pk_fma_f32 v[90:91], v[110:111], v[54:55], v[96:97] op_sel:[0,1,0]
	v_pk_fma_f32 v[76:77], v[76:77], v[54:55], v[80:81] op_sel:[0,1,0]
	v_cvt_pk_f32_fp8_e32 v[80:81], v78
	v_cvt_pk_f32_fp8_sdwa v[96:97], v78 src0_sel:WORD_1
	v_cvt_pk_f32_fp8_e32 v[108:109], v79
	v_cvt_pk_f32_fp8_sdwa v[78:79], v79 src0_sel:WORD_1
	v_pk_fma_f32 v[80:81], v[80:81], v[54:55], v[84:85] op_sel:[0,1,0]
	v_pk_fma_f32 v[84:85], v[96:97], v[54:55], v[88:89] op_sel:[0,1,0]
	v_pk_fma_f32 v[88:89], v[108:109], v[54:55], v[98:99] op_sel:[0,1,0]
	v_pk_fma_f32 v[52:53], v[78:79], v[54:55], v[52:53] op_sel:[0,1,0]
	v_cvt_pk_f32_fp8_e32 v[54:55], v64
	v_cvt_pk_f32_fp8_sdwa v[78:79], v64 src0_sel:WORD_1
	v_cvt_pk_f32_fp8_e32 v[96:97], v65
	v_cvt_pk_f32_fp8_sdwa v[64:65], v65 src0_sel:WORD_1
	v_pk_fma_f32 v[54:55], v[54:55], v[28:29], v[82:83] op_sel_hi:[1,0,1]
	v_pk_fma_f32 v[78:79], v[78:79], v[28:29], v[86:87] op_sel_hi:[1,0,1]
	v_pk_fma_f32 v[82:83], v[96:97], v[28:29], v[90:91] op_sel_hi:[1,0,1]
	v_pk_fma_f32 v[64:65], v[64:65], v[28:29], v[76:77] op_sel_hi:[1,0,1]
	v_cvt_pk_f32_fp8_e32 v[76:77], v66
	v_cvt_pk_f32_fp8_sdwa v[86:87], v66 src0_sel:WORD_1
	v_cvt_pk_f32_fp8_e32 v[90:91], v67
	v_cvt_pk_f32_fp8_sdwa v[66:67], v67 src0_sel:WORD_1
	v_pk_fma_f32 v[76:77], v[76:77], v[28:29], v[80:81] op_sel_hi:[1,0,1]
	v_pk_fma_f32 v[80:81], v[86:87], v[28:29], v[84:85] op_sel_hi:[1,0,1]
	v_pk_fma_f32 v[84:85], v[90:91], v[28:29], v[88:89] op_sel_hi:[1,0,1]
	v_pk_fma_f32 v[52:53], v[66:67], v[28:29], v[52:53] op_sel_hi:[1,0,1]
	v_cvt_pk_f32_fp8_e32 v[66:67], v56
	v_cvt_pk_f32_fp8_sdwa v[86:87], v56 src0_sel:WORD_1
	v_cvt_pk_f32_fp8_e32 v[88:89], v57
	v_cvt_pk_f32_fp8_sdwa v[56:57], v57 src0_sel:WORD_1
	v_pk_fma_f32 v[54:55], v[66:67], v[28:29], v[54:55] op_sel:[0,1,0]
	v_pk_fma_f32 v[66:67], v[86:87], v[28:29], v[78:79] op_sel:[0,1,0]
	v_pk_fma_f32 v[78:79], v[88:89], v[28:29], v[82:83] op_sel:[0,1,0]
	v_pk_fma_f32 v[56:57], v[56:57], v[28:29], v[64:65] op_sel:[0,1,0]
	v_cvt_pk_f32_fp8_e32 v[64:65], v58
	v_cvt_pk_f32_fp8_sdwa v[82:83], v58 src0_sel:WORD_1
	v_cvt_pk_f32_fp8_e32 v[86:87], v59
	v_cvt_pk_f32_fp8_sdwa v[58:59], v59 src0_sel:WORD_1
	v_pk_fma_f32 v[64:65], v[64:65], v[28:29], v[76:77] op_sel:[0,1,0]
	v_pk_fma_f32 v[76:77], v[82:83], v[28:29], v[80:81] op_sel:[0,1,0]
	v_pk_fma_f32 v[80:81], v[86:87], v[28:29], v[84:85] op_sel:[0,1,0]
	v_pk_fma_f32 v[28:29], v[58:59], v[28:29], v[52:53] op_sel:[0,1,0]
	v_cvt_pk_f32_fp8_e32 v[52:53], v48
	v_cvt_pk_f32_fp8_sdwa v[58:59], v48 src0_sel:WORD_1
	v_cvt_pk_f32_fp8_e32 v[82:83], v49
	v_cvt_pk_f32_fp8_sdwa v[48:49], v49 src0_sel:WORD_1
	v_pk_fma_f32 v[52:53], v[52:53], v[30:31], v[54:55] op_sel_hi:[1,0,1]
	v_pk_fma_f32 v[54:55], v[58:59], v[30:31], v[66:67] op_sel_hi:[1,0,1]
	v_pk_fma_f32 v[58:59], v[82:83], v[30:31], v[78:79] op_sel_hi:[1,0,1]
	v_pk_fma_f32 v[48:49], v[48:49], v[30:31], v[56:57] op_sel_hi:[1,0,1]
	v_cvt_pk_f32_fp8_e32 v[56:57], v50
	v_cvt_pk_f32_fp8_sdwa v[66:67], v50 src0_sel:WORD_1
	v_cvt_pk_f32_fp8_e32 v[78:79], v51
	v_cvt_pk_f32_fp8_sdwa v[50:51], v51 src0_sel:WORD_1
	v_pk_fma_f32 v[56:57], v[56:57], v[30:31], v[64:65] op_sel_hi:[1,0,1]
	v_pk_fma_f32 v[64:65], v[66:67], v[30:31], v[76:77] op_sel_hi:[1,0,1]
	v_pk_fma_f32 v[66:67], v[78:79], v[30:31], v[80:81] op_sel_hi:[1,0,1]
	v_pk_fma_f32 v[28:29], v[50:51], v[30:31], v[28:29] op_sel_hi:[1,0,1]
	v_cvt_pk_f32_fp8_e32 v[50:51], v44
	v_cvt_pk_f32_fp8_sdwa v[76:77], v44 src0_sel:WORD_1
	v_cvt_pk_f32_fp8_e32 v[78:79], v45
	v_cvt_pk_f32_fp8_sdwa v[44:45], v45 src0_sel:WORD_1
	v_pk_fma_f32 v[50:51], v[50:51], v[30:31], v[52:53] op_sel:[0,1,0]
	v_pk_fma_f32 v[52:53], v[76:77], v[30:31], v[54:55] op_sel:[0,1,0]
	v_pk_fma_f32 v[54:55], v[78:79], v[30:31], v[58:59] op_sel:[0,1,0]
	v_pk_fma_f32 v[44:45], v[44:45], v[30:31], v[48:49] op_sel:[0,1,0]
	v_cvt_pk_f32_fp8_e32 v[48:49], v46
	v_cvt_pk_f32_fp8_sdwa v[58:59], v46 src0_sel:WORD_1
	v_cvt_pk_f32_fp8_e32 v[76:77], v47
	v_cvt_pk_f32_fp8_sdwa v[46:47], v47 src0_sel:WORD_1
	v_pk_fma_f32 v[48:49], v[48:49], v[30:31], v[56:57] op_sel:[0,1,0]
	v_pk_fma_f32 v[56:57], v[58:59], v[30:31], v[64:65] op_sel:[0,1,0]
	v_pk_fma_f32 v[58:59], v[76:77], v[30:31], v[66:67] op_sel:[0,1,0]
; DI void peer_v_phase(const Params& p) {
;     ...
; #pragma unroll
;     for (int i = 0; i < 16; ++i) {
;       const float wi = (i & 3) == 0 ? r.w[i >> 2].x : (i & 3) == 1 ? r.w[i >> 2].y : (i & 3) == 2 ? r.w[i >> 2].z : r.w[i >> 2].w;
;       const f32x2 w2 = {wi, wi};
; #pragma unroll
;       for (int j = 0; j < 4; ++j) {
;         const f32x2 lo = __builtin_amdgcn_cvt_pk_f32_fp8((int)r.v[i][j], false);
;         const f32x2 hi = __builtin_amdgcn_cvt_pk_f32_fp8((int)r.v[i][j], true);
;         o2[2 * j] = __builtin_elementwise_fma(lo, w2, o2[2 * j]);
;         o2[2 * j + 1] = __builtin_elementwise_fma(hi, w2, o2[2 * j + 1]);
;       }
;     }
;     ...
;     float* xr = p.out + (size_t)tok * 1024 + 128 * g + 16 * s + 2 * q;
;     float2 y = *(const float2*)xr;
	v_pk_fma_f32 v[28:29], v[46:47], v[30:31], v[28:29] op_sel:[0,1,0]
	v_cvt_pk_f32_fp8_e32 v[30:31], v40
	v_cvt_pk_f32_fp8_sdwa v[46:47], v40 src0_sel:WORD_1
	v_cvt_pk_f32_fp8_e32 v[64:65], v41
	v_cvt_pk_f32_fp8_sdwa v[40:41], v41 src0_sel:WORD_1
	v_pk_fma_f32 v[30:31], v[30:31], v[12:13], v[50:51] op_sel_hi:[1,0,1]
	v_pk_fma_f32 v[46:47], v[46:47], v[12:13], v[52:53] op_sel_hi:[1,0,1]
	v_pk_fma_f32 v[50:51], v[64:65], v[12:13], v[54:55] op_sel_hi:[1,0,1]
	v_pk_fma_f32 v[40:41], v[40:41], v[12:13], v[44:45] op_sel_hi:[1,0,1]
	v_cvt_pk_f32_fp8_e32 v[44:45], v42
	v_cvt_pk_f32_fp8_sdwa v[52:53], v42 src0_sel:WORD_1
	v_cvt_pk_f32_fp8_e32 v[54:55], v43
	v_cvt_pk_f32_fp8_sdwa v[42:43], v43 src0_sel:WORD_1
	v_pk_fma_f32 v[44:45], v[44:45], v[12:13], v[48:49] op_sel_hi:[1,0,1]
	v_pk_fma_f32 v[48:49], v[52:53], v[12:13], v[56:57] op_sel_hi:[1,0,1]
	v_pk_fma_f32 v[52:53], v[54:55], v[12:13], v[58:59] op_sel_hi:[1,0,1]
	v_pk_fma_f32 v[28:29], v[42:43], v[12:13], v[28:29] op_sel_hi:[1,0,1]
	v_cvt_pk_f32_fp8_e32 v[42:43], v36
	v_cvt_pk_f32_fp8_sdwa v[54:55], v36 src0_sel:WORD_1
	v_cvt_pk_f32_fp8_e32 v[56:57], v37
	v_cvt_pk_f32_fp8_sdwa v[36:37], v37 src0_sel:WORD_1
	v_pk_fma_f32 v[30:31], v[42:43], v[12:13], v[30:31] op_sel:[0,1,0]
	v_pk_fma_f32 v[42:43], v[54:55], v[12:13], v[46:47] op_sel:[0,1,0]
	v_pk_fma_f32 v[46:47], v[56:57], v[12:13], v[50:51] op_sel:[0,1,0]
	v_pk_fma_f32 v[36:37], v[36:37], v[12:13], v[40:41] op_sel:[0,1,0]
	v_cvt_pk_f32_fp8_e32 v[40:41], v38
	v_cvt_pk_f32_fp8_sdwa v[50:51], v38 src0_sel:WORD_1
	v_cvt_pk_f32_fp8_e32 v[54:55], v39
	v_cvt_pk_f32_fp8_sdwa v[38:39], v39 src0_sel:WORD_1
	v_pk_fma_f32 v[40:41], v[40:41], v[12:13], v[44:45] op_sel:[0,1,0]
	v_pk_fma_f32 v[44:45], v[50:51], v[12:13], v[48:49] op_sel:[0,1,0]
	v_pk_fma_f32 v[48:49], v[54:55], v[12:13], v[52:53] op_sel:[0,1,0]
	v_pk_fma_f32 v[12:13], v[38:39], v[12:13], v[28:29] op_sel:[0,1,0]
	v_cvt_pk_f32_fp8_e32 v[28:29], v32
	v_cvt_pk_f32_fp8_sdwa v[38:39], v32 src0_sel:WORD_1
	v_cvt_pk_f32_fp8_e32 v[50:51], v33
	v_cvt_pk_f32_fp8_sdwa v[32:33], v33 src0_sel:WORD_1
	v_pk_fma_f32 v[28:29], v[28:29], v[14:15], v[30:31] op_sel_hi:[1,0,1]
	v_pk_fma_f32 v[30:31], v[38:39], v[14:15], v[42:43] op_sel_hi:[1,0,1]
	v_pk_fma_f32 v[38:39], v[50:51], v[14:15], v[46:47] op_sel_hi:[1,0,1]
	v_pk_fma_f32 v[32:33], v[32:33], v[14:15], v[36:37] op_sel_hi:[1,0,1]
	v_cvt_pk_f32_fp8_e32 v[36:37], v34
	v_cvt_pk_f32_fp8_sdwa v[42:43], v34 src0_sel:WORD_1
	v_cvt_pk_f32_fp8_e32 v[46:47], v35
	v_cvt_pk_f32_fp8_sdwa v[34:35], v35 src0_sel:WORD_1
	v_pk_fma_f32 v[36:37], v[36:37], v[14:15], v[40:41] op_sel_hi:[1,0,1]
	v_pk_fma_f32 v[40:41], v[42:43], v[14:15], v[44:45] op_sel_hi:[1,0,1]
	v_pk_fma_f32 v[42:43], v[46:47], v[14:15], v[48:49] op_sel_hi:[1,0,1]
	v_pk_fma_f32 v[12:13], v[34:35], v[14:15], v[12:13] op_sel_hi:[1,0,1]
	v_cvt_pk_f32_fp8_e32 v[34:35], v24
	v_cvt_pk_f32_fp8_sdwa v[44:45], v24 src0_sel:WORD_1
	v_cvt_pk_f32_fp8_e32 v[46:47], v25
	v_cvt_pk_f32_fp8_sdwa v[24:25], v25 src0_sel:WORD_1
	v_pk_fma_f32 v[28:29], v[34:35], v[14:15], v[28:29] op_sel:[0,1,0]
	v_pk_fma_f32 v[30:31], v[44:45], v[14:15], v[30:31] op_sel:[0,1,0]
	v_pk_fma_f32 v[34:35], v[46:47], v[14:15], v[38:39] op_sel:[0,1,0]
	v_pk_fma_f32 v[24:25], v[24:25], v[14:15], v[32:33] op_sel:[0,1,0]
	v_cvt_pk_f32_fp8_e32 v[32:33], v26
	v_cvt_pk_f32_fp8_sdwa v[38:39], v26 src0_sel:WORD_1
	v_cvt_pk_f32_fp8_e32 v[44:45], v27
	v_cvt_pk_f32_fp8_sdwa v[26:27], v27 src0_sel:WORD_1
	v_pk_fma_f32 v[32:33], v[32:33], v[14:15], v[36:37] op_sel:[0,1,0]
	v_pk_fma_f32 v[36:37], v[38:39], v[14:15], v[40:41] op_sel:[0,1,0]
	v_pk_fma_f32 v[38:39], v[44:45], v[14:15], v[42:43] op_sel:[0,1,0]
	v_pk_fma_f32 v[12:13], v[26:27], v[14:15], v[12:13] op_sel:[0,1,0]
	v_cvt_pk_f32_fp8_e32 v[14:15], v20
	v_cvt_pk_f32_fp8_sdwa v[26:27], v20 src0_sel:WORD_1
	v_cvt_pk_f32_fp8_e32 v[40:41], v21
	v_cvt_pk_f32_fp8_sdwa v[20:21], v21 src0_sel:WORD_1
	v_pk_fma_f32 v[14:15], v[14:15], v[0:1], v[28:29] op_sel_hi:[1,0,1]
	v_pk_fma_f32 v[26:27], v[26:27], v[0:1], v[30:31] op_sel_hi:[1,0,1]
	v_pk_fma_f32 v[28:29], v[40:41], v[0:1], v[34:35] op_sel_hi:[1,0,1]
	v_pk_fma_f32 v[20:21], v[20:21], v[0:1], v[24:25] op_sel_hi:[1,0,1]
	v_cvt_pk_f32_fp8_e32 v[24:25], v22
	v_cvt_pk_f32_fp8_sdwa v[30:31], v22 src0_sel:WORD_1
	v_cvt_pk_f32_fp8_e32 v[34:35], v23
	v_cvt_pk_f32_fp8_sdwa v[22:23], v23 src0_sel:WORD_1
	v_pk_fma_f32 v[24:25], v[24:25], v[0:1], v[32:33] op_sel_hi:[1,0,1]
	v_pk_fma_f32 v[30:31], v[30:31], v[0:1], v[36:37] op_sel_hi:[1,0,1]
	v_pk_fma_f32 v[32:33], v[34:35], v[0:1], v[38:39] op_sel_hi:[1,0,1]
	v_pk_fma_f32 v[12:13], v[22:23], v[0:1], v[12:13] op_sel_hi:[1,0,1]
	v_cvt_pk_f32_fp8_e32 v[22:23], v16
	v_cvt_pk_f32_fp8_sdwa v[34:35], v16 src0_sel:WORD_1
	v_cvt_pk_f32_fp8_e32 v[36:37], v17
	v_cvt_pk_f32_fp8_sdwa v[16:17], v17 src0_sel:WORD_1
	v_pk_fma_f32 v[14:15], v[22:23], v[0:1], v[14:15] op_sel:[0,1,0]
	v_pk_fma_f32 v[22:23], v[34:35], v[0:1], v[26:27] op_sel:[0,1,0]
	v_pk_fma_f32 v[26:27], v[36:37], v[0:1], v[28:29] op_sel:[0,1,0]
	v_pk_fma_f32 v[16:17], v[16:17], v[0:1], v[20:21] op_sel:[0,1,0]
	v_cvt_pk_f32_fp8_e32 v[20:21], v18
	v_cvt_pk_f32_fp8_sdwa v[28:29], v18 src0_sel:WORD_1
	v_cvt_pk_f32_fp8_e32 v[34:35], v19
	v_ashrrev_i32_e32 v205, 31, v204
	v_pk_fma_f32 v[20:21], v[20:21], v[0:1], v[24:25] op_sel:[0,1,0]
	v_pk_fma_f32 v[24:25], v[28:29], v[0:1], v[30:31] op_sel:[0,1,0]
	v_pk_fma_f32 v[28:29], v[34:35], v[0:1], v[32:33] op_sel:[0,1,0]
	v_lshlrev_b64 v[32:33], 12, v[204:205]
	v_lshl_add_u64 v[32:33], v[202:203], 0, v[32:33]
	global_load_dwordx2 v[34:35], v[32:33], off
	v_cvt_pk_f32_fp8_sdwa v[18:19], v19 src0_sel:WORD_1
	v_cvt_pk_f32_fp8_e32 v[30:31], v9
; DI float wave_sum(float v) {
; #pragma unroll
;   for (int o = 32; o >= 1; o >>= 1) v += __shfl_xor(v, o);
;   return v;
; DI void peer_v_phase(const Params& p) {
;     ...
;     float o[16];
; #pragma unroll
;     for (int k = 0; k < 8; ++k) { o[2 * k] = o2[k][0]; o[2 * k + 1] = o2[k][1]; }
;     float r8[8], r4[4], r2[2];
; #pragma unroll
;     for (int k = 0; k < 8; ++k) {
;       const float keep = (lane & 32) ? o[k + 8] : o[k], send = (lane & 32) ? o[k] : o[k + 8];
;       r8[k] = keep + __shfl_xor(send, 32);
;     }
; #pragma unroll
;     for (int k = 0; k < 4; ++k) {
;       const float keep = (lane & 16) ? r8[k + 4] : r8[k], send = (lane & 16) ? r8[k] : r8[k + 4];
;       r4[k] = keep + __shfl_xor(send, 16);
;     }
; #pragma unroll
;     for (int k = 0; k < 2; ++k) {
;       const float keep = (lane & 8) ? r4[k + 2] : r4[k], send = (lane & 8) ? r4[k] : r4[k + 2];
;       r2[k] = keep + __shfl_xor(send, 8);
;     }
;     float* xr = p.out + (size_t)tok * 1024 + 128 * g + 16 * s + 2 * q;
;     float2 y = *(const float2*)xr;
;     y.x += r2[0]; y.y += r2[1];
;     *(float2*)xr = y;
;     const float ss = wave_sum(y.x * y.x + y.y * y.y);
;     if (lane == 0) SSP[tok] = ss;
	v_pk_fma_f32 v[0:1], v[18:19], v[0:1], v[12:13] op_sel:[0,1,0]
	v_cvt_pk_f32_fp8_e32 v[12:13], v8
	v_cvt_pk_f32_fp8_sdwa v[18:19], v8 src0_sel:WORD_1
	v_cvt_pk_f32_fp8_sdwa v[8:9], v9 src0_sel:WORD_1
	v_pk_fma_f32 v[12:13], v[12:13], v[2:3], v[14:15] op_sel_hi:[1,0,1]
	v_pk_fma_f32 v[14:15], v[18:19], v[2:3], v[22:23] op_sel_hi:[1,0,1]
	v_pk_fma_f32 v[18:19], v[30:31], v[2:3], v[26:27] op_sel_hi:[1,0,1]
	v_pk_fma_f32 v[8:9], v[8:9], v[2:3], v[16:17] op_sel_hi:[1,0,1]
	v_cvt_pk_f32_fp8_e32 v[16:17], v10
	v_cvt_pk_f32_fp8_sdwa v[22:23], v10 src0_sel:WORD_1
	v_cvt_pk_f32_fp8_e32 v[26:27], v11
	v_cvt_pk_f32_fp8_sdwa v[10:11], v11 src0_sel:WORD_1
	v_pk_fma_f32 v[16:17], v[16:17], v[2:3], v[20:21] op_sel_hi:[1,0,1]
	v_pk_fma_f32 v[20:21], v[22:23], v[2:3], v[24:25] op_sel_hi:[1,0,1]
	v_pk_fma_f32 v[22:23], v[26:27], v[2:3], v[28:29] op_sel_hi:[1,0,1]
	v_pk_fma_f32 v[0:1], v[10:11], v[2:3], v[0:1] op_sel_hi:[1,0,1]
	v_cvt_pk_f32_fp8_e32 v[10:11], v4
	v_cvt_pk_f32_fp8_sdwa v[24:25], v4 src0_sel:WORD_1
	v_cvt_pk_f32_fp8_e32 v[26:27], v5
	v_cvt_pk_f32_fp8_sdwa v[4:5], v5 src0_sel:WORD_1
	v_pk_fma_f32 v[10:11], v[10:11], v[2:3], v[12:13] op_sel:[0,1,0]
	v_pk_fma_f32 v[12:13], v[24:25], v[2:3], v[14:15] op_sel:[0,1,0]
	v_pk_fma_f32 v[14:15], v[26:27], v[2:3], v[18:19] op_sel:[0,1,0]
	v_pk_fma_f32 v[4:5], v[4:5], v[2:3], v[8:9] op_sel:[0,1,0]
	v_cvt_pk_f32_fp8_e32 v[8:9], v6
	v_cvt_pk_f32_fp8_sdwa v[18:19], v6 src0_sel:WORD_1
	v_cvt_pk_f32_fp8_e32 v[24:25], v7
	v_cvt_pk_f32_fp8_sdwa v[6:7], v7 src0_sel:WORD_1
	v_pk_fma_f32 v[8:9], v[8:9], v[2:3], v[16:17] op_sel:[0,1,0]
	v_pk_fma_f32 v[16:17], v[18:19], v[2:3], v[20:21] op_sel:[0,1,0]
	v_pk_fma_f32 v[18:19], v[24:25], v[2:3], v[22:23] op_sel:[0,1,0]
	v_pk_fma_f32 v[0:1], v[6:7], v[2:3], v[0:1] op_sel:[0,1,0]
	v_cndmask_b32_e32 v2, v10, v8, vcc
	v_cndmask_b32_e32 v3, v11, v9, vcc
	ds_bpermute_b32 v2, v210, v2
	ds_bpermute_b32 v3, v210, v3
	v_cndmask_b32_e32 v6, v12, v16, vcc
	v_cndmask_b32_e32 v7, v13, v17, vcc
	ds_bpermute_b32 v6, v210, v6
	ds_bpermute_b32 v7, v210, v7
	v_cndmask_b32_e32 v20, v14, v18, vcc
	v_cndmask_b32_e32 v21, v15, v19, vcc
	ds_bpermute_b32 v20, v210, v20
	ds_bpermute_b32 v21, v210, v21
	v_cndmask_b32_e32 v22, v4, v0, vcc
	v_cndmask_b32_e32 v23, v5, v1, vcc
	ds_bpermute_b32 v22, v210, v22
	ds_bpermute_b32 v23, v210, v23
	v_cndmask_b32_e32 v9, v9, v11, vcc
	v_cndmask_b32_e32 v8, v8, v10, vcc
	s_waitcnt lgkmcnt(6)
	v_pk_add_f32 v[2:3], v[8:9], v[2:3]
	v_cndmask_b32_e32 v9, v17, v13, vcc
	v_cndmask_b32_e32 v8, v16, v12, vcc
	s_waitcnt lgkmcnt(4)
	v_pk_add_f32 v[6:7], v[8:9], v[6:7]
	v_cndmask_b32_e32 v9, v19, v15, vcc
	v_cndmask_b32_e32 v8, v18, v14, vcc
	s_waitcnt lgkmcnt(2)
	v_pk_add_f32 v[8:9], v[8:9], v[20:21]
	v_cndmask_b32_e32 v1, v1, v5, vcc
	v_cndmask_b32_e32 v0, v0, v4, vcc
	s_waitcnt lgkmcnt(0)
	v_pk_add_f32 v[0:1], v[0:1], v[22:23]
	v_cndmask_b32_e64 v11, v9, v3, s[2:3]
	v_cndmask_b32_e64 v3, v3, v9, s[2:3]
	ds_bpermute_b32 v5, v211, v3
	v_cndmask_b32_e64 v3, v6, v0, s[2:3]
	v_cndmask_b32_e64 v4, v2, v8, s[2:3]
	ds_bpermute_b32 v12, v211, v3
	v_cndmask_b32_e64 v3, v7, v1, s[2:3]
	ds_bpermute_b32 v4, v211, v4
	ds_bpermute_b32 v13, v211, v3
	v_cndmask_b32_e64 v10, v8, v2, s[2:3]
	v_cndmask_b32_e64 v1, v1, v7, s[2:3]
	v_cndmask_b32_e64 v0, v0, v6, s[2:3]
	s_waitcnt lgkmcnt(1)
	v_pk_add_f32 v[2:3], v[10:11], v[4:5]
	s_waitcnt lgkmcnt(0)
	v_pk_add_f32 v[0:1], v[0:1], v[12:13]
	s_nop 0
	v_cndmask_b32_e64 v4, v2, v0, s[4:5]
	v_cndmask_b32_e64 v5, v3, v1, s[4:5]
	ds_bpermute_b32 v4, v212, v4
	ds_bpermute_b32 v5, v212, v5
	v_cndmask_b32_e64 v1, v1, v3, s[4:5]
	v_cndmask_b32_e64 v0, v0, v2, s[4:5]
	s_waitcnt lgkmcnt(0)
	v_pk_add_f32 v[0:1], v[0:1], v[4:5]
	s_waitcnt vmcnt(0)
	v_pk_add_f32 v[2:3], v[0:1], v[34:35]
	global_store_dwordx2 v[32:33], v[2:3], off
	v_pk_mul_f32 v[0:1], v[2:3], v[2:3]
	s_nop 0
	v_add_f32_e32 v0, v0, v1
	s_nop 1
	v_add_f32_dpp v0, v0, v0 quad_perm:[1,0,3,2] row_mask:0xf bank_mask:0xf
	s_nop 1
	v_add_f32_dpp v0, v0, v0 quad_perm:[2,3,0,1] row_mask:0xf bank_mask:0xf
	s_nop 1
	v_add_f32_dpp v0, v0, v0 row_half_mirror row_mask:0xf bank_mask:0xf
	s_nop 1
	v_add_f32_dpp v0, v0, v0 row_mirror row_mask:0xf bank_mask:0xf
	s_nop 1
	v_add_f32_dpp v0, v0, v0 row_bcast:15 row_mask:0xa bank_mask:0xf
	s_nop 1
	v_add_f32_dpp v0, v0, v0 row_bcast:31 row_mask:0xc bank_mask:0xf
	s_and_saveexec_b64 s[8:9], s[6:7]
	s_cbranch_execz .LBB0_1479
	v_mov_b32_e32 v2, v0
	v_lshl_add_u64 v[0:1], v[204:205], 2, s[12:13]
	global_store_dword v[0:1], v2, off
; DI void peer_v_phase(const Params& p) {
;     ...
;   auto gather = [&](PeerVRows& r, const int* e, int tok) {
; #pragma unroll
;     for (int i = 0; i < 16; ++i) r.v[i] = *(const u32x4*)(Vb + (size_t)e[i] * 128);
;     const float4* wp = (const float4*)(W + (size_t)tok * 128 + 16 * q);
; #pragma unroll
;     for (int j = 0; j < 4; ++j) r.w[j] = wp[j];
;   };
;   auto compute = [&](const PeerVRows& r, int tok) {
;     f32x2 o2[8];
; #pragma unroll
;     for (int k = 0; k < 8; ++k) { o2[k][0] = 0.f; o2[k][1] = 0.f; }
; #pragma unroll
;     for (int i = 0; i < 16; ++i) {
;       const float wi = (i & 3) == 0 ? r.w[i >> 2].x : (i & 3) == 1 ? r.w[i >> 2].y : (i & 3) == 2 ? r.w[i >> 2].z : r.w[i >> 2].w;
;       const f32x2 w2 = {wi, wi};
; #pragma unroll
;       for (int j = 0; j < 4; ++j) {
;         const f32x2 lo = __builtin_amdgcn_cvt_pk_f32_fp8((int)r.v[i][j], false);
;         const f32x2 hi = __builtin_amdgcn_cvt_pk_f32_fp8((int)r.v[i][j], true);
;         o2[2 * j] = __builtin_elementwise_fma(lo, w2, o2[2 * j]);
;         o2[2 * j + 1] = __builtin_elementwise_fma(hi, w2, o2[2 * j + 1]);
;       }
;     }
;     ...
;     peer_load_e(eb, EID, tokof(k + 3), q);
;     gather(ga, ea, tokof(k + 2));
;     __builtin_amdgcn_sched_barrier(0);
;     if (k + 1 < n) compute(gb, tokof(k + 1));
.LBB0_1479:
	s_or_b64 exec, exec, s[8:9]
	v_min_i32_e32 v0, s1, v195
	s_waitcnt lgkmcnt(0)
	v_mad_u64_u32 v[0:1], s[8:9], v0, s18, v[194:195]
	v_ashrrev_i32_e32 v1, 31, v0
	v_lshlrev_b64 v[0:1], 9, v[0:1]
	v_lshl_add_u64 v[0:1], v[198:199], 0, v[0:1]
	global_load_dwordx4 v[96:99], v[0:1], off offset:48
	global_load_dwordx4 v[108:111], v[0:1], off offset:32
	global_load_dwordx4 v[116:119], v[0:1], off offset:16
	global_load_dwordx4 v[132:135], v[0:1], off
	v_ashrrev_i32_e32 v1, 31, v188
	v_mov_b32_e32 v0, v188
	v_ashrrev_i32_e32 v3, 31, v189
	v_mov_b32_e32 v2, v189
	v_lshlrev_b64 v[0:1], 7, v[0:1]
	v_lshlrev_b64 v[2:3], 7, v[2:3]
	v_lshl_add_u64 v[0:1], v[196:197], 0, v[0:1]
	v_lshl_add_u64 v[2:3], v[196:197], 0, v[2:3]
	global_load_dwordx4 v[88:91], v[0:1], off
	global_load_dwordx4 v[84:87], v[2:3], off
	v_ashrrev_i32_e32 v1, 31, v190
	v_mov_b32_e32 v0, v190
	v_ashrrev_i32_e32 v3, 31, v191
	v_mov_b32_e32 v2, v191
	v_lshlrev_b64 v[0:1], 7, v[0:1]
	v_lshlrev_b64 v[2:3], 7, v[2:3]
	v_lshl_add_u64 v[0:1], v[196:197], 0, v[0:1]
	v_lshl_add_u64 v[2:3], v[196:197], 0, v[2:3]
	global_load_dwordx4 v[80:83], v[0:1], off
	global_load_dwordx4 v[76:79], v[2:3], off
	v_ashrrev_i32_e32 v1, 31, v184
	v_mov_b32_e32 v0, v184
	v_ashrrev_i32_e32 v3, 31, v185
	v_mov_b32_e32 v2, v185
	v_lshlrev_b64 v[0:1], 7, v[0:1]
	v_lshlrev_b64 v[2:3], 7, v[2:3]
	v_lshl_add_u64 v[0:1], v[196:197], 0, v[0:1]
	v_lshl_add_u64 v[2:3], v[196:197], 0, v[2:3]
	global_load_dwordx4 v[64:67], v[0:1], off
	global_load_dwordx4 v[56:59], v[2:3], off
	v_ashrrev_i32_e32 v1, 31, v186
	v_mov_b32_e32 v0, v186
	v_ashrrev_i32_e32 v3, 31, v187
	v_mov_b32_e32 v2, v187
	v_lshlrev_b64 v[0:1], 7, v[0:1]
	v_lshlrev_b64 v[2:3], 7, v[2:3]
	v_lshl_add_u64 v[0:1], v[196:197], 0, v[0:1]
	v_lshl_add_u64 v[2:3], v[196:197], 0, v[2:3]
	global_load_dwordx4 v[48:51], v[0:1], off
	global_load_dwordx4 v[44:47], v[2:3], off
	v_ashrrev_i32_e32 v1, 31, v176
	v_mov_b32_e32 v0, v176
	v_ashrrev_i32_e32 v3, 31, v177
	v_mov_b32_e32 v2, v177
	v_lshlrev_b64 v[0:1], 7, v[0:1]
	v_lshlrev_b64 v[2:3], 7, v[2:3]
	v_lshl_add_u64 v[0:1], v[196:197], 0, v[0:1]
	v_lshl_add_u64 v[2:3], v[196:197], 0, v[2:3]
	global_load_dwordx4 v[40:43], v[0:1], off
	global_load_dwordx4 v[36:39], v[2:3], off
	v_ashrrev_i32_e32 v1, 31, v178
	v_mov_b32_e32 v0, v178
	v_ashrrev_i32_e32 v3, 31, v179
	v_mov_b32_e32 v2, v179
	v_lshlrev_b64 v[0:1], 7, v[0:1]
	v_lshlrev_b64 v[2:3], 7, v[2:3]
	v_lshl_add_u64 v[0:1], v[196:197], 0, v[0:1]
	v_lshl_add_u64 v[2:3], v[196:197], 0, v[2:3]
	global_load_dwordx4 v[32:35], v[0:1], off
	global_load_dwordx4 v[24:27], v[2:3], off
	v_ashrrev_i32_e32 v1, 31, v172
	v_mov_b32_e32 v0, v172
	v_ashrrev_i32_e32 v3, 31, v173
	v_mov_b32_e32 v2, v173
	v_lshlrev_b64 v[0:1], 7, v[0:1]
	v_lshlrev_b64 v[2:3], 7, v[2:3]
	v_lshl_add_u64 v[0:1], v[196:197], 0, v[0:1]
	v_lshl_add_u64 v[2:3], v[196:197], 0, v[2:3]
	global_load_dwordx4 v[20:23], v[0:1], off
	global_load_dwordx4 v[16:19], v[2:3], off
	v_ashrrev_i32_e32 v1, 31, v174
	v_mov_b32_e32 v0, v174
	v_ashrrev_i32_e32 v3, 31, v175
	v_mov_b32_e32 v2, v175
	v_lshlrev_b64 v[0:1], 7, v[0:1]
	v_lshlrev_b64 v[2:3], 7, v[2:3]
	v_lshl_add_u64 v[0:1], v[196:197], 0, v[0:1]
	v_lshl_add_u64 v[2:3], v[196:197], 0, v[2:3]
	v_lshl_add_u64 v[52:53], v[200:201], 0, v[208:209]
	global_load_dwordx4 v[8:11], v[0:1], off
	global_load_dwordx4 v[4:7], v[2:3], off
	s_nop 0
	global_load_dwordx4 v[0:3], v[52:53], off offset:48
	global_load_dwordx4 v[12:15], v[52:53], off offset:32
	global_load_dwordx4 v[28:31], v[52:53], off offset:16
	s_nop 0
	global_load_dwordx4 v[52:55], v[52:53], off
	v_cmp_lt_i32_e64 s[8:9], s16, v193
	s_and_saveexec_b64 s[16:17], s[8:9]
	s_cbranch_execz .LBB0_1476
	v_cvt_pk_f32_fp8_e32 v[172:173], v168
	v_cvt_pk_f32_fp8_sdwa v[174:175], v168 src0_sel:WORD_1
	v_cvt_pk_f32_fp8_e32 v[176:177], v169
	v_cvt_pk_f32_fp8_sdwa v[168:169], v169 src0_sel:WORD_1
	v_cvt_pk_f32_fp8_e32 v[188:189], v164
	v_cvt_pk_f32_fp8_sdwa v[190:191], v164 src0_sel:WORD_1
	v_cvt_pk_f32_fp8_e32 v[208:209], v165
	v_cvt_pk_f32_fp8_sdwa v[164:165], v165 src0_sel:WORD_1
	v_pk_fma_f32 v[172:173], v[172:173], v[180:181], 0 op_sel_hi:[1,0,0]
	v_pk_fma_f32 v[174:175], v[174:175], v[180:181], 0 op_sel_hi:[1,0,0]
	v_pk_fma_f32 v[168:169], v[168:169], v[180:181], 0 op_sel_hi:[1,0,0]
	v_cvt_pk_f32_fp8_e32 v[178:179], v170
	v_cvt_pk_f32_fp8_sdwa v[184:185], v170 src0_sel:WORD_1
	v_cvt_pk_f32_fp8_e32 v[186:187], v171
	v_cvt_pk_f32_fp8_sdwa v[170:171], v171 src0_sel:WORD_1
	v_pk_fma_f32 v[172:173], v[188:189], v[180:181], v[172:173] op_sel:[0,1,0]
	v_pk_fma_f32 v[174:175], v[190:191], v[180:181], v[174:175] op_sel:[0,1,0]
	v_pk_fma_f32 v[164:165], v[164:165], v[180:181], v[168:169] op_sel:[0,1,0]
	v_cvt_pk_f32_fp8_e32 v[168:169], v166
	v_cvt_pk_f32_fp8_sdwa v[188:189], v166 src0_sel:WORD_1
	v_cvt_pk_f32_fp8_e32 v[190:191], v167
	v_cvt_pk_f32_fp8_sdwa v[166:167], v167 src0_sel:WORD_1
	v_pk_fma_f32 v[176:177], v[176:177], v[180:181], 0 op_sel_hi:[1,0,0]
	v_pk_fma_f32 v[178:179], v[178:179], v[180:181], 0 op_sel_hi:[1,0,0]
	v_pk_fma_f32 v[184:185], v[184:185], v[180:181], 0 op_sel_hi:[1,0,0]
	v_pk_fma_f32 v[186:187], v[186:187], v[180:181], 0 op_sel_hi:[1,0,0]
	v_pk_fma_f32 v[170:171], v[170:171], v[180:181], 0 op_sel_hi:[1,0,0]
	v_pk_fma_f32 v[176:177], v[208:209], v[180:181], v[176:177] op_sel:[0,1,0]
	v_pk_fma_f32 v[168:169], v[168:169], v[180:181], v[178:179] op_sel:[0,1,0]
	v_pk_fma_f32 v[178:179], v[188:189], v[180:181], v[184:185] op_sel:[0,1,0]
	v_pk_fma_f32 v[184:185], v[190:191], v[180:181], v[186:187] op_sel:[0,1,0]
	v_pk_fma_f32 v[166:167], v[166:167], v[180:181], v[170:171] op_sel:[0,1,0]
	v_cvt_pk_f32_fp8_e32 v[170:171], v160
; DI void peer_v_phase(const Params& p) {
;     ...
; #pragma unroll
;     for (int i = 0; i < 16; ++i) {
;       const float wi = (i & 3) == 0 ? r.w[i >> 2].x : (i & 3) == 1 ? r.w[i >> 2].y : (i & 3) == 2 ? r.w[i >> 2].z : r.w[i >> 2].w;
;       const f32x2 w2 = {wi, wi};
; #pragma unroll
;       for (int j = 0; j < 4; ++j) {
;         const f32x2 lo = __builtin_amdgcn_cvt_pk_f32_fp8((int)r.v[i][j], false);
;         const f32x2 hi = __builtin_amdgcn_cvt_pk_f32_fp8((int)r.v[i][j], true);
;         o2[2 * j] = __builtin_elementwise_fma(lo, w2, o2[2 * j]);
;         o2[2 * j + 1] = __builtin_elementwise_fma(hi, w2, o2[2 * j + 1]);
;       }
;     }
	v_cvt_pk_f32_fp8_sdwa v[180:181], v160 src0_sel:WORD_1
	v_cvt_pk_f32_fp8_e32 v[186:187], v161
	v_cvt_pk_f32_fp8_sdwa v[160:161], v161 src0_sel:WORD_1
	v_pk_fma_f32 v[170:171], v[170:171], v[182:183], v[172:173] op_sel_hi:[1,0,1]
	v_pk_fma_f32 v[172:173], v[180:181], v[182:183], v[174:175] op_sel_hi:[1,0,1]
	v_pk_fma_f32 v[174:175], v[186:187], v[182:183], v[176:177] op_sel_hi:[1,0,1]
	v_pk_fma_f32 v[160:161], v[160:161], v[182:183], v[164:165] op_sel_hi:[1,0,1]
	v_cvt_pk_f32_fp8_e32 v[164:165], v162
	v_cvt_pk_f32_fp8_sdwa v[176:177], v162 src0_sel:WORD_1
	v_cvt_pk_f32_fp8_e32 v[180:181], v163
	v_cvt_pk_f32_fp8_sdwa v[162:163], v163 src0_sel:WORD_1
	v_pk_fma_f32 v[164:165], v[164:165], v[182:183], v[168:169] op_sel_hi:[1,0,1]
	v_pk_fma_f32 v[168:169], v[176:177], v[182:183], v[178:179] op_sel_hi:[1,0,1]
	v_pk_fma_f32 v[176:177], v[180:181], v[182:183], v[184:185] op_sel_hi:[1,0,1]
	v_pk_fma_f32 v[162:163], v[162:163], v[182:183], v[166:167] op_sel_hi:[1,0,1]
	v_mov_b32_e32 v166, v183
	v_cvt_pk_f32_fp8_e32 v[178:179], v152
	v_cvt_pk_f32_fp8_sdwa v[180:181], v152 src0_sel:WORD_1
	v_cvt_pk_f32_fp8_e32 v[182:183], v153
	v_cvt_pk_f32_fp8_sdwa v[152:153], v153 src0_sel:WORD_1
	v_pk_fma_f32 v[170:171], v[178:179], v[166:167], v[170:171] op_sel_hi:[1,0,1]
	v_pk_fma_f32 v[172:173], v[180:181], v[166:167], v[172:173] op_sel_hi:[1,0,1]
	v_cvt_pk_f32_fp8_sdwa v[178:179], v154 src0_sel:WORD_1
	v_pk_fma_f32 v[152:153], v[152:153], v[166:167], v[160:161] op_sel_hi:[1,0,1]
	v_cvt_pk_f32_fp8_e32 v[160:161], v154
	v_cvt_pk_f32_fp8_e32 v[180:181], v155
	v_cvt_pk_f32_fp8_sdwa v[154:155], v155 src0_sel:WORD_1
	v_pk_fma_f32 v[174:175], v[182:183], v[166:167], v[174:175] op_sel_hi:[1,0,1]
	v_pk_fma_f32 v[160:161], v[160:161], v[166:167], v[164:165] op_sel_hi:[1,0,1]
	v_pk_fma_f32 v[164:165], v[178:179], v[166:167], v[168:169] op_sel_hi:[1,0,1]
	v_pk_fma_f32 v[168:169], v[180:181], v[166:167], v[176:177] op_sel_hi:[1,0,1]
	v_pk_fma_f32 v[154:155], v[154:155], v[166:167], v[162:163] op_sel_hi:[1,0,1]
	v_cvt_pk_f32_fp8_e32 v[162:163], v148
	v_cvt_pk_f32_fp8_sdwa v[166:167], v148 src0_sel:WORD_1
	v_cvt_pk_f32_fp8_e32 v[176:177], v149
	v_cvt_pk_f32_fp8_sdwa v[148:149], v149 src0_sel:WORD_1
	v_pk_fma_f32 v[162:163], v[162:163], v[156:157], v[170:171] op_sel_hi:[1,0,1]
	v_pk_fma_f32 v[166:167], v[166:167], v[156:157], v[172:173] op_sel_hi:[1,0,1]
	v_pk_fma_f32 v[170:171], v[176:177], v[156:157], v[174:175] op_sel_hi:[1,0,1]
	v_pk_fma_f32 v[148:149], v[148:149], v[156:157], v[152:153] op_sel_hi:[1,0,1]
	v_cvt_pk_f32_fp8_e32 v[152:153], v150
	v_cvt_pk_f32_fp8_sdwa v[172:173], v150 src0_sel:WORD_1
	v_cvt_pk_f32_fp8_e32 v[174:175], v151
	v_cvt_pk_f32_fp8_sdwa v[150:151], v151 src0_sel:WORD_1
	v_pk_fma_f32 v[152:153], v[152:153], v[156:157], v[160:161] op_sel_hi:[1,0,1]
	v_pk_fma_f32 v[160:161], v[172:173], v[156:157], v[164:165] op_sel_hi:[1,0,1]
	v_pk_fma_f32 v[164:165], v[174:175], v[156:157], v[168:169] op_sel_hi:[1,0,1]
	v_pk_fma_f32 v[150:151], v[150:151], v[156:157], v[154:155] op_sel_hi:[1,0,1]
	v_mov_b32_e32 v154, v157
	v_cvt_pk_f32_fp8_e32 v[156:157], v144
	v_cvt_pk_f32_fp8_sdwa v[168:169], v144 src0_sel:WORD_1
	v_cvt_pk_f32_fp8_e32 v[172:173], v145
	v_cvt_pk_f32_fp8_sdwa v[144:145], v145 src0_sel:WORD_1
	v_pk_fma_f32 v[156:157], v[156:157], v[154:155], v[162:163] op_sel_hi:[1,0,1]
	v_pk_fma_f32 v[162:163], v[168:169], v[154:155], v[166:167] op_sel_hi:[1,0,1]
	v_pk_fma_f32 v[166:167], v[172:173], v[154:155], v[170:171] op_sel_hi:[1,0,1]
	v_pk_fma_f32 v[144:145], v[144:145], v[154:155], v[148:149] op_sel_hi:[1,0,1]
	v_cvt_pk_f32_fp8_e32 v[148:149], v146
	v_cvt_pk_f32_fp8_sdwa v[168:169], v146 src0_sel:WORD_1
	v_cvt_pk_f32_fp8_e32 v[170:171], v147
	v_cvt_pk_f32_fp8_sdwa v[146:147], v147 src0_sel:WORD_1
	v_pk_fma_f32 v[148:149], v[148:149], v[154:155], v[152:153] op_sel_hi:[1,0,1]
	v_pk_fma_f32 v[152:153], v[168:169], v[154:155], v[160:161] op_sel_hi:[1,0,1]
	v_pk_fma_f32 v[160:161], v[170:171], v[154:155], v[164:165] op_sel_hi:[1,0,1]
	v_pk_fma_f32 v[146:147], v[146:147], v[154:155], v[150:151] op_sel_hi:[1,0,1]
	v_cvt_pk_f32_fp8_e32 v[150:151], v140
	v_cvt_pk_f32_fp8_sdwa v[154:155], v140 src0_sel:WORD_1
	v_cvt_pk_f32_fp8_e32 v[164:165], v141
	v_cvt_pk_f32_fp8_sdwa v[140:141], v141 src0_sel:WORD_1
	v_pk_fma_f32 v[150:151], v[150:151], v[158:159], v[156:157] op_sel_hi:[1,0,1]
	v_pk_fma_f32 v[154:155], v[154:155], v[158:159], v[162:163] op_sel_hi:[1,0,1]
	v_pk_fma_f32 v[156:157], v[164:165], v[158:159], v[166:167] op_sel_hi:[1,0,1]
	v_pk_fma_f32 v[140:141], v[140:141], v[158:159], v[144:145] op_sel_hi:[1,0,1]
	v_cvt_pk_f32_fp8_e32 v[144:145], v142
	v_cvt_pk_f32_fp8_sdwa v[162:163], v142 src0_sel:WORD_1
	v_cvt_pk_f32_fp8_e32 v[164:165], v143
	v_cvt_pk_f32_fp8_sdwa v[142:143], v143 src0_sel:WORD_1
	v_pk_fma_f32 v[144:145], v[144:145], v[158:159], v[148:149] op_sel_hi:[1,0,1]
	v_pk_fma_f32 v[148:149], v[162:163], v[158:159], v[152:153] op_sel_hi:[1,0,1]
	v_pk_fma_f32 v[152:153], v[164:165], v[158:159], v[160:161] op_sel_hi:[1,0,1]
	v_pk_fma_f32 v[142:143], v[142:143], v[158:159], v[146:147] op_sel_hi:[1,0,1]
	v_mov_b32_e32 v146, v159
	v_cvt_pk_f32_fp8_e32 v[158:159], v136
	v_cvt_pk_f32_fp8_sdwa v[160:161], v136 src0_sel:WORD_1
	v_cvt_pk_f32_fp8_e32 v[162:163], v137
	v_cvt_pk_f32_fp8_sdwa v[136:137], v137 src0_sel:WORD_1
	v_pk_fma_f32 v[150:151], v[158:159], v[146:147], v[150:151] op_sel_hi:[1,0,1]
	v_pk_fma_f32 v[154:155], v[160:161], v[146:147], v[154:155] op_sel_hi:[1,0,1]
	v_cvt_pk_f32_fp8_sdwa v[158:159], v138 src0_sel:WORD_1
	v_pk_fma_f32 v[136:137], v[136:137], v[146:147], v[140:141] op_sel_hi:[1,0,1]
	v_cvt_pk_f32_fp8_e32 v[140:141], v138
; DI void peer_v_phase(const Params& p) {
;     ...
; #pragma unroll
;     for (int i = 0; i < 16; ++i) {
;       const float wi = (i & 3) == 0 ? r.w[i >> 2].x : (i & 3) == 1 ? r.w[i >> 2].y : (i & 3) == 2 ? r.w[i >> 2].z : r.w[i >> 2].w;
;       const f32x2 w2 = {wi, wi};
; #pragma unroll
;       for (int j = 0; j < 4; ++j) {
;         const f32x2 lo = __builtin_amdgcn_cvt_pk_f32_fp8((int)r.v[i][j], false);
;         const f32x2 hi = __builtin_amdgcn_cvt_pk_f32_fp8((int)r.v[i][j], true);
;         o2[2 * j] = __builtin_elementwise_fma(lo, w2, o2[2 * j]);
;         o2[2 * j + 1] = __builtin_elementwise_fma(hi, w2, o2[2 * j + 1]);
;       }
;     }
	v_cvt_pk_f32_fp8_e32 v[160:161], v139
	v_cvt_pk_f32_fp8_sdwa v[138:139], v139 src0_sel:WORD_1
	v_pk_fma_f32 v[156:157], v[162:163], v[146:147], v[156:157] op_sel_hi:[1,0,1]
	v_pk_fma_f32 v[140:141], v[140:141], v[146:147], v[144:145] op_sel_hi:[1,0,1]
	v_pk_fma_f32 v[144:145], v[158:159], v[146:147], v[148:149] op_sel_hi:[1,0,1]
	v_pk_fma_f32 v[148:149], v[160:161], v[146:147], v[152:153] op_sel_hi:[1,0,1]
	v_pk_fma_f32 v[138:139], v[138:139], v[146:147], v[142:143] op_sel_hi:[1,0,1]
	v_cvt_pk_f32_fp8_e32 v[142:143], v128
	v_cvt_pk_f32_fp8_sdwa v[146:147], v128 src0_sel:WORD_1
	v_cvt_pk_f32_fp8_e32 v[152:153], v129
	v_cvt_pk_f32_fp8_sdwa v[128:129], v129 src0_sel:WORD_1
	v_pk_fma_f32 v[142:143], v[142:143], v[124:125], v[150:151] op_sel_hi:[1,0,1]
	v_pk_fma_f32 v[146:147], v[146:147], v[124:125], v[154:155] op_sel_hi:[1,0,1]
	v_pk_fma_f32 v[150:151], v[152:153], v[124:125], v[156:157] op_sel_hi:[1,0,1]
	v_pk_fma_f32 v[128:129], v[128:129], v[124:125], v[136:137] op_sel_hi:[1,0,1]
	v_cvt_pk_f32_fp8_e32 v[136:137], v130
	v_cvt_pk_f32_fp8_sdwa v[152:153], v130 src0_sel:WORD_1
	v_cvt_pk_f32_fp8_e32 v[154:155], v131
	v_cvt_pk_f32_fp8_sdwa v[130:131], v131 src0_sel:WORD_1
	v_pk_fma_f32 v[136:137], v[136:137], v[124:125], v[140:141] op_sel_hi:[1,0,1]
	v_pk_fma_f32 v[140:141], v[152:153], v[124:125], v[144:145] op_sel_hi:[1,0,1]
	v_pk_fma_f32 v[144:145], v[154:155], v[124:125], v[148:149] op_sel_hi:[1,0,1]
	v_pk_fma_f32 v[130:131], v[130:131], v[124:125], v[138:139] op_sel_hi:[1,0,1]
	v_cvt_pk_f32_fp8_e32 v[138:139], v120
	v_cvt_pk_f32_fp8_sdwa v[148:149], v120 src0_sel:WORD_1
	v_cvt_pk_f32_fp8_e32 v[152:153], v121
	v_cvt_pk_f32_fp8_sdwa v[120:121], v121 src0_sel:WORD_1
	v_mov_b32_e32 v124, v125
	v_pk_fma_f32 v[138:139], v[138:139], v[124:125], v[142:143] op_sel_hi:[1,0,1]
	v_pk_fma_f32 v[142:143], v[148:149], v[124:125], v[146:147] op_sel_hi:[1,0,1]
	v_pk_fma_f32 v[146:147], v[152:153], v[124:125], v[150:151] op_sel_hi:[1,0,1]
	v_pk_fma_f32 v[120:121], v[120:121], v[124:125], v[128:129] op_sel_hi:[1,0,1]
	v_cvt_pk_f32_fp8_e32 v[128:129], v122
	v_cvt_pk_f32_fp8_sdwa v[148:149], v122 src0_sel:WORD_1
	v_cvt_pk_f32_fp8_e32 v[150:151], v123
	v_cvt_pk_f32_fp8_sdwa v[122:123], v123 src0_sel:WORD_1
	v_pk_fma_f32 v[128:129], v[128:129], v[124:125], v[136:137] op_sel_hi:[1,0,1]
	v_pk_fma_f32 v[136:137], v[148:149], v[124:125], v[140:141] op_sel_hi:[1,0,1]
	v_pk_fma_f32 v[140:141], v[150:151], v[124:125], v[144:145] op_sel_hi:[1,0,1]
	v_pk_fma_f32 v[122:123], v[122:123], v[124:125], v[130:131] op_sel_hi:[1,0,1]
	v_cvt_pk_f32_fp8_e32 v[124:125], v112
	v_cvt_pk_f32_fp8_sdwa v[130:131], v112 src0_sel:WORD_1
	v_cvt_pk_f32_fp8_e32 v[144:145], v113
	v_cvt_pk_f32_fp8_sdwa v[112:113], v113 src0_sel:WORD_1
	v_pk_fma_f32 v[124:125], v[124:125], v[126:127], v[138:139] op_sel_hi:[1,0,1]
	v_pk_fma_f32 v[130:131], v[130:131], v[126:127], v[142:143] op_sel_hi:[1,0,1]
	v_pk_fma_f32 v[138:139], v[144:145], v[126:127], v[146:147] op_sel_hi:[1,0,1]
	v_pk_fma_f32 v[112:113], v[112:113], v[126:127], v[120:121] op_sel_hi:[1,0,1]
	v_cvt_pk_f32_fp8_e32 v[120:121], v114
	v_cvt_pk_f32_fp8_sdwa v[142:143], v114 src0_sel:WORD_1
	v_cvt_pk_f32_fp8_e32 v[144:145], v115
	v_cvt_pk_f32_fp8_sdwa v[114:115], v115 src0_sel:WORD_1
	v_pk_fma_f32 v[120:121], v[120:121], v[126:127], v[128:129] op_sel_hi:[1,0,1]
	v_pk_fma_f32 v[128:129], v[142:143], v[126:127], v[136:137] op_sel_hi:[1,0,1]
	v_pk_fma_f32 v[136:137], v[144:145], v[126:127], v[140:141] op_sel_hi:[1,0,1]
	v_pk_fma_f32 v[114:115], v[114:115], v[126:127], v[122:123] op_sel_hi:[1,0,1]
	v_cvt_pk_f32_fp8_e32 v[122:123], v104
	v_cvt_pk_f32_fp8_sdwa v[140:141], v104 src0_sel:WORD_1
	v_cvt_pk_f32_fp8_e32 v[142:143], v105
	v_cvt_pk_f32_fp8_sdwa v[104:105], v105 src0_sel:WORD_1
	v_mov_b32_e32 v126, v127
	v_pk_fma_f32 v[122:123], v[122:123], v[126:127], v[124:125] op_sel_hi:[1,0,1]
	v_pk_fma_f32 v[124:125], v[140:141], v[126:127], v[130:131] op_sel_hi:[1,0,1]
	v_pk_fma_f32 v[130:131], v[142:143], v[126:127], v[138:139] op_sel_hi:[1,0,1]
	v_cvt_pk_f32_fp8_e32 v[138:139], v106
	v_pk_fma_f32 v[104:105], v[104:105], v[126:127], v[112:113] op_sel_hi:[1,0,1]
	v_cvt_pk_f32_fp8_sdwa v[112:113], v106 src0_sel:WORD_1
	v_cvt_pk_f32_fp8_e32 v[140:141], v107
	v_cvt_pk_f32_fp8_sdwa v[106:107], v107 src0_sel:WORD_1
	v_pk_fma_f32 v[120:121], v[138:139], v[126:127], v[120:121] op_sel_hi:[1,0,1]
	v_pk_fma_f32 v[112:113], v[112:113], v[126:127], v[128:129] op_sel_hi:[1,0,1]
	v_pk_fma_f32 v[128:129], v[140:141], v[126:127], v[136:137] op_sel_hi:[1,0,1]
	v_pk_fma_f32 v[106:107], v[106:107], v[126:127], v[114:115] op_sel_hi:[1,0,1]
	v_cvt_pk_f32_fp8_sdwa v[114:115], v100 src0_sel:WORD_1
	v_cvt_pk_f32_fp8_e32 v[126:127], v101
	v_cvt_pk_f32_fp8_e32 v[136:137], v100
	v_cvt_pk_f32_fp8_sdwa v[100:101], v101 src0_sel:WORD_1
	v_pk_fma_f32 v[114:115], v[114:115], v[72:73], v[124:125] op_sel_hi:[1,0,1]
	v_pk_fma_f32 v[124:125], v[126:127], v[72:73], v[130:131] op_sel_hi:[1,0,1]
	v_cvt_pk_f32_fp8_e32 v[126:127], v102
	v_pk_fma_f32 v[100:101], v[100:101], v[72:73], v[104:105] op_sel_hi:[1,0,1]
	v_cvt_pk_f32_fp8_sdwa v[104:105], v102 src0_sel:WORD_1
	v_cvt_pk_f32_fp8_e32 v[130:131], v103
	v_cvt_pk_f32_fp8_sdwa v[102:103], v103 src0_sel:WORD_1
	v_pk_fma_f32 v[120:121], v[126:127], v[72:73], v[120:121] op_sel_hi:[1,0,1]
	v_cvt_pk_f32_fp8_e32 v[126:127], v92
	v_pk_fma_f32 v[122:123], v[136:137], v[72:73], v[122:123] op_sel_hi:[1,0,1]
	v_pk_fma_f32 v[102:103], v[102:103], v[72:73], v[106:107] op_sel_hi:[1,0,1]
	v_cvt_pk_f32_fp8_sdwa v[106:107], v92 src0_sel:WORD_1
	v_pk_fma_f32 v[104:105], v[104:105], v[72:73], v[112:113] op_sel_hi:[1,0,1]
; DI float wave_sum(float v) {
; #pragma unroll
;   for (int o = 32; o >= 1; o >>= 1) v += __shfl_xor(v, o);
;   return v;
; DI void peer_v_phase(const Params& p) {
;     ...
; #pragma unroll
;     for (int i = 0; i < 16; ++i) {
;       const float wi = (i & 3) == 0 ? r.w[i >> 2].x : (i & 3) == 1 ? r.w[i >> 2].y : (i & 3) == 2 ? r.w[i >> 2].z : r.w[i >> 2].w;
;       const f32x2 w2 = {wi, wi};
; #pragma unroll
;       for (int j = 0; j < 4; ++j) {
;         const f32x2 lo = __builtin_amdgcn_cvt_pk_f32_fp8((int)r.v[i][j], false);
;         const f32x2 hi = __builtin_amdgcn_cvt_pk_f32_fp8((int)r.v[i][j], true);
;         o2[2 * j] = __builtin_elementwise_fma(lo, w2, o2[2 * j]);
;         o2[2 * j + 1] = __builtin_elementwise_fma(hi, w2, o2[2 * j + 1]);
;       }
;     }
;     float o[16];
; #pragma unroll
;     for (int k = 0; k < 8; ++k) { o[2 * k] = o2[k][0]; o[2 * k + 1] = o2[k][1]; }
;     float r8[8], r4[4], r2[2];
; #pragma unroll
;     for (int k = 0; k < 8; ++k) {
;       const float keep = (lane & 32) ? o[k + 8] : o[k], send = (lane & 32) ? o[k] : o[k + 8];
;       r8[k] = keep + __shfl_xor(send, 32);
;     }
; #pragma unroll
;     for (int k = 0; k < 4; ++k) {
;       const float keep = (lane & 16) ? r8[k + 4] : r8[k], send = (lane & 16) ? r8[k] : r8[k + 4];
;       r4[k] = keep + __shfl_xor(send, 16);
;     }
; #pragma unroll
;     for (int k = 0; k < 2; ++k) {
;       const float keep = (lane & 8) ? r4[k + 2] : r4[k], send = (lane & 8) ? r4[k] : r4[k + 2];
;       r2[k] = keep + __shfl_xor(send, 8);
;     }
;     float* xr = p.out + (size_t)tok * 1024 + 128 * g + 16 * s + 2 * q;
;     float2 y = *(const float2*)xr;
;     y.x += r2[0]; y.y += r2[1];
;     *(float2*)xr = y;
;     const float ss = wave_sum(y.x * y.x + y.y * y.y);
;     if (lane == 0) SSP[tok] = ss;
	v_pk_fma_f32 v[112:113], v[130:131], v[72:73], v[128:129] op_sel_hi:[1,0,1]
	v_mov_b32_e32 v72, v73
	v_pk_fma_f32 v[122:123], v[126:127], v[72:73], v[122:123] op_sel_hi:[1,0,1]
	v_cvt_pk_f32_fp8_e32 v[126:127], v93
	v_cvt_pk_f32_fp8_sdwa v[92:93], v93 src0_sel:WORD_1
	v_pk_fma_f32 v[106:107], v[106:107], v[72:73], v[114:115] op_sel_hi:[1,0,1]
	v_cvt_pk_f32_fp8_e32 v[114:115], v94
	v_pk_fma_f32 v[124:125], v[126:127], v[72:73], v[124:125] op_sel_hi:[1,0,1]
	v_pk_fma_f32 v[92:93], v[92:93], v[72:73], v[100:101] op_sel_hi:[1,0,1]
	v_cvt_pk_f32_fp8_sdwa v[100:101], v94 src0_sel:WORD_1
	v_pk_fma_f32 v[114:115], v[114:115], v[72:73], v[120:121] op_sel_hi:[1,0,1]
	v_cvt_pk_f32_fp8_e32 v[120:121], v95
	v_cvt_pk_f32_fp8_sdwa v[94:95], v95 src0_sel:WORD_1
	v_pk_fma_f32 v[100:101], v[100:101], v[72:73], v[104:105] op_sel_hi:[1,0,1]
	v_cvt_pk_f32_fp8_e32 v[104:105], v68
	v_pk_fma_f32 v[112:113], v[120:121], v[72:73], v[112:113] op_sel_hi:[1,0,1]
	v_lshlrev_b64 v[120:121], 12, v[206:207]
	v_lshl_add_u64 v[120:121], v[202:203], 0, v[120:121]
	v_pk_fma_f32 v[72:73], v[94:95], v[72:73], v[102:103] op_sel_hi:[1,0,1]
	v_pk_fma_f32 v[102:103], v[104:105], v[74:75], v[122:123] op_sel_hi:[1,0,1]
	global_load_dwordx2 v[122:123], v[120:121], off
	v_cvt_pk_f32_fp8_sdwa v[94:95], v68 src0_sel:WORD_1
	v_cvt_pk_f32_fp8_e32 v[104:105], v69
	v_cvt_pk_f32_fp8_sdwa v[68:69], v69 src0_sel:WORD_1
	v_pk_fma_f32 v[94:95], v[94:95], v[74:75], v[106:107] op_sel_hi:[1,0,1]
	v_pk_fma_f32 v[104:105], v[104:105], v[74:75], v[124:125] op_sel_hi:[1,0,1]
	v_pk_fma_f32 v[68:69], v[68:69], v[74:75], v[92:93] op_sel_hi:[1,0,1]
	v_cvt_pk_f32_fp8_e32 v[92:93], v70
	v_cvt_pk_f32_fp8_sdwa v[106:107], v70 src0_sel:WORD_1
	v_cvt_pk_f32_fp8_e32 v[124:125], v71
	v_cvt_pk_f32_fp8_sdwa v[70:71], v71 src0_sel:WORD_1
	v_pk_fma_f32 v[92:93], v[92:93], v[74:75], v[114:115] op_sel_hi:[1,0,1]
	v_pk_fma_f32 v[100:101], v[106:107], v[74:75], v[100:101] op_sel_hi:[1,0,1]
	v_pk_fma_f32 v[106:107], v[124:125], v[74:75], v[112:113] op_sel_hi:[1,0,1]
	v_pk_fma_f32 v[70:71], v[70:71], v[74:75], v[72:73] op_sel_hi:[1,0,1]
	v_mov_b32_e32 v72, v75
	v_cvt_pk_f32_fp8_e32 v[74:75], v60
	v_cvt_pk_f32_fp8_sdwa v[112:113], v60 src0_sel:WORD_1
	v_cvt_pk_f32_fp8_e32 v[114:115], v61
	v_cvt_pk_f32_fp8_sdwa v[60:61], v61 src0_sel:WORD_1
	v_pk_fma_f32 v[74:75], v[74:75], v[72:73], v[102:103] op_sel_hi:[1,0,1]
	v_pk_fma_f32 v[94:95], v[112:113], v[72:73], v[94:95] op_sel_hi:[1,0,1]
	v_pk_fma_f32 v[102:103], v[114:115], v[72:73], v[104:105] op_sel_hi:[1,0,1]
	v_pk_fma_f32 v[60:61], v[60:61], v[72:73], v[68:69] op_sel_hi:[1,0,1]
	v_cvt_pk_f32_fp8_e32 v[68:69], v62
	v_cvt_pk_f32_fp8_sdwa v[104:105], v62 src0_sel:WORD_1
	v_cvt_pk_f32_fp8_e32 v[112:113], v63
	v_cvt_pk_f32_fp8_sdwa v[62:63], v63 src0_sel:WORD_1
	v_pk_fma_f32 v[68:69], v[68:69], v[72:73], v[92:93] op_sel_hi:[1,0,1]
	v_pk_fma_f32 v[92:93], v[104:105], v[72:73], v[100:101] op_sel_hi:[1,0,1]
	v_pk_fma_f32 v[100:101], v[112:113], v[72:73], v[106:107] op_sel_hi:[1,0,1]
	v_pk_fma_f32 v[62:63], v[62:63], v[72:73], v[70:71] op_sel_hi:[1,0,1]
	v_cndmask_b32_e32 v70, v74, v68, vcc
	v_cndmask_b32_e32 v71, v75, v69, vcc
	ds_bpermute_b32 v70, v210, v70
	ds_bpermute_b32 v71, v210, v71
	v_cndmask_b32_e32 v72, v94, v92, vcc
	v_cndmask_b32_e32 v73, v95, v93, vcc
	ds_bpermute_b32 v72, v210, v72
	ds_bpermute_b32 v73, v210, v73
	v_cndmask_b32_e32 v104, v102, v100, vcc
	v_cndmask_b32_e32 v105, v103, v101, vcc
	v_cndmask_b32_e32 v106, v60, v62, vcc
	v_cndmask_b32_e32 v107, v61, v63, vcc
	ds_bpermute_b32 v104, v210, v104
	ds_bpermute_b32 v105, v210, v105
	ds_bpermute_b32 v106, v210, v106
	ds_bpermute_b32 v107, v210, v107
	v_cndmask_b32_e32 v69, v69, v75, vcc
	v_cndmask_b32_e32 v68, v68, v74, vcc
	s_waitcnt lgkmcnt(6)
	v_pk_add_f32 v[68:69], v[68:69], v[70:71]
	v_cndmask_b32_e32 v71, v93, v95, vcc
	v_cndmask_b32_e32 v70, v92, v94, vcc
	s_waitcnt lgkmcnt(4)
	v_pk_add_f32 v[70:71], v[70:71], v[72:73]
	v_cndmask_b32_e32 v73, v101, v103, vcc
	v_cndmask_b32_e32 v72, v100, v102, vcc
	v_cndmask_b32_e32 v61, v63, v61, vcc
	v_cndmask_b32_e32 v60, v62, v60, vcc
	s_waitcnt lgkmcnt(2)
	v_pk_add_f32 v[72:73], v[72:73], v[104:105]
	s_waitcnt lgkmcnt(0)
	v_pk_add_f32 v[60:61], v[60:61], v[106:107]
	v_cndmask_b32_e64 v75, v73, v69, s[2:3]
	v_cndmask_b32_e64 v63, v69, v73, s[2:3]
	v_cndmask_b32_e64 v69, v70, v60, s[2:3]
	v_cndmask_b32_e64 v62, v68, v72, s[2:3]
	ds_bpermute_b32 v92, v211, v69
	v_cndmask_b32_e64 v69, v71, v61, s[2:3]
	ds_bpermute_b32 v62, v211, v62
	ds_bpermute_b32 v63, v211, v63
	ds_bpermute_b32 v93, v211, v69
	v_cndmask_b32_e64 v74, v72, v68, s[2:3]
	v_cndmask_b32_e64 v61, v61, v71, s[2:3]
	v_cndmask_b32_e64 v60, v60, v70, s[2:3]
	s_waitcnt lgkmcnt(1)
	v_pk_add_f32 v[62:63], v[74:75], v[62:63]
	s_waitcnt lgkmcnt(0)
	v_pk_add_f32 v[60:61], v[60:61], v[92:93]
	s_nop 0
	v_cndmask_b32_e64 v68, v62, v60, s[4:5]
	v_cndmask_b32_e64 v69, v63, v61, s[4:5]
	ds_bpermute_b32 v68, v212, v68
	ds_bpermute_b32 v69, v212, v69
	v_cndmask_b32_e64 v61, v61, v63, s[4:5]
	v_cndmask_b32_e64 v60, v60, v62, s[4:5]
	s_waitcnt lgkmcnt(0)
	v_pk_add_f32 v[60:61], v[60:61], v[68:69]
	s_waitcnt vmcnt(0)
	v_pk_add_f32 v[62:63], v[60:61], v[122:123]
	global_store_dwordx2 v[120:121], v[62:63], off
	v_pk_mul_f32 v[60:61], v[62:63], v[62:63]
	s_nop 0
	v_add_f32_e32 v60, v60, v61
	s_nop 1
	v_add_f32_dpp v60, v60, v60 quad_perm:[1,0,3,2] row_mask:0xf bank_mask:0xf
	s_nop 1
	v_add_f32_dpp v60, v60, v60 quad_perm:[2,3,0,1] row_mask:0xf bank_mask:0xf
	s_nop 1
	v_add_f32_dpp v60, v60, v60 row_half_mirror row_mask:0xf bank_mask:0xf
	s_nop 1
	v_add_f32_dpp v60, v60, v60 row_mirror row_mask:0xf bank_mask:0xf
	s_nop 1
	v_add_f32_dpp v60, v60, v60 row_bcast:15 row_mask:0xa bank_mask:0xf
	s_nop 1
	v_add_f32_dpp v60, v60, v60 row_bcast:31 row_mask:0xc bank_mask:0xf
	s_and_b64 exec, exec, s[6:7]
	s_cbranch_execz .LBB0_1476
	v_mov_b32_e32 v62, v60
	v_lshl_add_u64 v[60:61], v[206:207], 2, s[12:13]
	global_store_dword v[60:61], v62, off
	s_branch .LBB0_1476
